# speedup vs baseline: 1.0068x; 1.0068x over previous
; __device__ __forceinline__ unsigned pack2(float a, float b) { return (unsigned)f2bf(a) | ((unsigned)f2bf(b) << 16); }
; __device__ __forceinline__ float siluf(float x) { return x / (1.f + __expf(-x)); }
; #define UNPACK8(q, f)                                                                                   \
;   float f##0 = lo16(q.x), f##1 = hi16(q.x), f##2 = lo16(q.y), f##3 = hi16(q.y), f##4 = lo16(q.z),        \
;         f##5 = hi16(q.z), f##6 = lo16(q.w), f##7 = hi16(q.w)
; __device__ __forceinline__ void phase_ssd_conv(const Params& p, int layer) {
;     ...
;     float h[3][8];
;     int tstart = c * 128 + rg * 16;
; #pragma unroll
;     for (int i = 0; i < 3; i++) {
;       int tt = tstart - 3 + i;
;       if (tt >= NPADR) {
;         u32x4 q = *(const u32x4*)(raw + (size_t)tt * 2048 + cv);
;         UNPACK8(q, f);
;         h[i][0] = f0; h[i][1] = f1; h[i][2] = f2; h[i][3] = f3; h[i][4] = f4; h[i][5] = f5; h[i][6] = f6; h[i][7] = f7;
;       } else {
; #pragma unroll
;         for (int j = 0; j < 8; j++) h[i][j] = 0.f;
;       }
;     }
; #pragma unroll 4
;     for (int rr = 0; rr < 16; rr++) {
;       int t = tstart + rr;
;       float cur[8];
;       bool vt = t >= NPADR;
;       if (vt) {
;         u32x4 q = *(const u32x4*)(raw + (size_t)t * 2048 + cv);
;         UNPACK8(q, f);
;         cur[0] = f0; cur[1] = f1; cur[2] = f2; cur[3] = f3; cur[4] = f4; cur[5] = f5; cur[6] = f6; cur[7] = f7;
;       } else {
; #pragma unroll
;         for (int j = 0; j < 8; j++) cur[j] = 0.f;
;       }
;       float o[8];
; #pragma unroll
;       for (int j = 0; j < 8; j++) {
;         float s = bias[j] + w[0][j] * h[0][j] + w[1][j] * h[1][j] + w[2][j] * h[2][j] + w[3][j] * cur[j];
;         s = siluf(s);
;         if (cv < 1024 && !vt) s = 0.f;
;         o[j] = s;
;         h[0][j] = h[1][j]; h[1][j] = h[2][j]; h[2][j] = cur[j];
;       }
;       u32x4 r;
;       r.x = pack2(o[0], o[1]); r.y = pack2(o[2], o[3]); r.z = pack2(o[4], o[5]); r.w = pack2(o[6], o[7]);
;       *(u32x4*)(xc + (size_t)t * 2048 + cv) = r;
.LBB0_775:
	s_or_b64 exec, exec, s[12:13]
	s_and_b32 s12, s41, 7
	s_cmp_gt_u32 s21, 3
	s_load_dwordx8 s[76:83], s[86:87], 0x80
	s_waitcnt vmcnt(1)
	v_mov_b32_e32 v51, v34
	v_mov_b32_e32 v34, v26
	v_mov_b32_e32 v26, v1
	v_mov_b32_e32 v1, v17
	v_mov_b32_e32 v64, v21
	v_mov_b32_e32 v21, v13
	v_mov_b32_e32 v65, v29
	s_waitcnt vmcnt(0)
	v_mov_b32_e32 v29, v37
	s_cselect_b64 s[24:25], -1, 0
	s_ashr_i32 s23, s22, 31
	v_mov_b32_e32 v1, v2
	v_mov_b32_e32 v29, v30
	v_mov_b32_e32 v21, v22
	v_mov_b32_e32 v2, v26
	v_mov_b32_e32 v30, v65
	v_mov_b32_e32 v22, v64
	v_mov_b32_e32 v26, v25
	v_mov_b32_e32 v25, v34
	v_mov_b32_e32 v34, v33
	v_mov_b32_e32 v33, v51
	v_lshl_add_u64 v[64:65], v[40:41], 0, s[22:23]
	v_mov_b32_e32 v51, v45
	v_lshl_or_b32 v44, s12, 9, v96
	v_lshlrev_b64 v[64:65], 12, v[64:65]
	v_lshlrev_b64 v[66:67], 12, v[50:51]
	v_mov_b32_e32 v52, v5
	v_mov_b32_e32 v5, v9
	v_or_b32_e32 v64, v64, v44
	v_or_b32_e32 v66, v66, v44
	v_swap_b32 v17, v18
	v_swap_b32 v37, v38
	v_swap_b32 v9, v10
	v_swap_b32 v13, v14
	v_mov_b32_e32 v5, v6
	v_mov_b32_e32 v6, v52
	s_waitcnt lgkmcnt(0)
	v_lshl_add_u64 v[64:65], s[82:83], 0, v[64:65]
	v_lshl_add_u64 v[66:67], s[82:83], 0, v[66:67]
	s_mov_b64 s[26:27], 0
	s_mov_b32 s99, 0
	s_mov_b32 s98, 0x11e81000
	v_lshl_add_u64 v[250:251], v[66:67], 0, s[98:99]
	global_load_dwordx4 v[106:109], v[250:251], off offset:-4096
	global_load_dwordx4 v[110:113], v[250:251], off
	s_mov_b32 s98, 0x11e83000
	v_lshl_add_u64 v[250:251], v[66:67], 0, s[98:99]
	global_load_dwordx4 v[114:117], v[250:251], off offset:-4096
	global_load_dwordx4 v[118:121], v[250:251], off
	s_mov_b32 s98, 0x11e85000
	v_lshl_add_u64 v[250:251], v[66:67], 0, s[98:99]
	global_load_dwordx4 v[122:125], v[250:251], off offset:-4096
	global_load_dwordx4 v[126:129], v[250:251], off
	s_mov_b32 s98, 0x11e87000
	v_lshl_add_u64 v[250:251], v[66:67], 0, s[98:99]
	global_load_dwordx4 v[130:133], v[250:251], off offset:-4096
	global_load_dwordx4 v[134:137], v[250:251], off
	s_mov_b32 s98, 0x11e89000
	v_lshl_add_u64 v[250:251], v[66:67], 0, s[98:99]
	global_load_dwordx4 v[138:141], v[250:251], off offset:-4096
	global_load_dwordx4 v[142:145], v[250:251], off
	s_mov_b32 s98, 0x11e8b000
	v_lshl_add_u64 v[250:251], v[66:67], 0, s[98:99]
	global_load_dwordx4 v[146:149], v[250:251], off offset:-4096
	global_load_dwordx4 v[150:153], v[250:251], off
	s_mov_b32 s98, 0x11e8d000
	v_lshl_add_u64 v[250:251], v[66:67], 0, s[98:99]
	global_load_dwordx4 v[154:157], v[250:251], off offset:-4096
	global_load_dwordx4 v[158:161], v[250:251], off
	s_mov_b32 s98, 0x11e8f000
	v_lshl_add_u64 v[250:251], v[66:67], 0, s[98:99]
	global_load_dwordx4 v[162:165], v[250:251], off offset:-4096
	global_load_dwordx4 v[166:169], v[250:251], off
	s_branch .LBB0_777
.LBB0_776:
	s_or_b64 exec, exec, s[28:29]
	v_pk_fma_f32 v[84:85], v[32:33], v[84:85], v[36:37]
	v_pk_fma_f32 v[82:83], v[34:35], v[82:83], v[38:39]
	v_pk_fma_f32 v[84:85], v[16:17], v[52:53], v[84:85]
	v_pk_fma_f32 v[82:83], v[18:19], v[68:69], v[82:83]
	v_pk_fma_f32 v[84:85], v[8:9], v[74:75], v[84:85]
	v_pk_fma_f32 v[82:83], v[10:11], v[72:73], v[82:83]
	v_pk_fma_f32 v[84:85], v[12:13], v[92:93], v[84:85]
	v_pk_fma_f32 v[82:83], v[14:15], v[76:77], v[82:83]
	v_mul_f32_e32 v44, 0xbfb8aa3b, v84
	v_exp_f32_e32 v86, v44
	v_mul_f32_e32 v44, 0xbfb8aa3b, v85
	v_exp_f32_e32 v87, v44
	v_mul_f32_e32 v90, 0xbfb8aa3b, v82
	v_exp_f32_e32 v90, v90
	v_pk_fma_f32 v[80:81], v[24:25], v[80:81], v[28:29]
	v_pk_add_f32 v[86:87], v[86:87], 1.0 op_sel_hi:[1,0]
	v_pk_fma_f32 v[80:81], v[0:1], v[56:57], v[80:81]
	v_div_scale_f32 v44, s[28:29], v86, v86, v84
	v_rcp_f32_e32 v51, v44
	v_pk_fma_f32 v[80:81], v[4:5], v[62:63], v[80:81]
	s_or_b64 s[12:13], s[24:25], s[12:13]
	v_pk_fma_f32 v[80:81], v[20:21], v[70:71], v[80:81]
	v_fma_f32 v91, -v44, v51, 1.0
	v_fmac_f32_e32 v51, v91, v51
	v_div_scale_f32 v91, vcc, v84, v86, v84
	v_mul_f32_e32 v99, v91, v51
	v_fma_f32 v100, -v44, v99, v91
	v_fmac_f32_e32 v99, v100, v51
	v_div_scale_f32 v100, s[28:29], v87, v87, v85
	v_fma_f32 v44, -v44, v99, v91
	v_rcp_f32_e32 v101, v100
	v_div_fmas_f32 v44, v44, v51, v99
	v_div_fixup_f32 v44, v44, v86, v84
	v_mul_f32_e32 v86, 0xbfb8aa3b, v83
	v_exp_f32_e32 v91, v86
	v_fma_f32 v51, -v100, v101, 1.0
	v_fmac_f32_e32 v101, v51, v101
	v_div_scale_f32 v51, vcc, v85, v87, v85
	v_mul_f32_e32 v84, v51, v101
	v_fma_f32 v86, -v100, v84, v51
	v_pk_add_f32 v[90:91], v[90:91], 1.0 op_sel_hi:[1,0]
	v_fmac_f32_e32 v84, v86, v101
	v_div_scale_f32 v86, s[28:29], v91, v91, v83
	v_rcp_f32_e32 v99, v86
	v_fma_f32 v51, -v100, v84, v51
	v_div_fmas_f32 v51, v51, v101, v84
	v_div_fixup_f32 v51, v51, v87, v85
	v_fma_f32 v84, -v86, v99, 1.0
	v_fmac_f32_e32 v99, v84, v99
	v_div_scale_f32 v84, vcc, v83, v91, v83
	v_mul_f32_e32 v85, v84, v99
	v_fma_f32 v87, -v86, v85, v84
	v_fmac_f32_e32 v85, v87, v99
	v_fma_f32 v84, -v86, v85, v84
	v_div_scale_f32 v86, s[28:29], v90, v90, v82
	v_rcp_f32_e32 v87, v86
	v_div_fmas_f32 v84, v84, v99, v85
	v_div_fixup_f32 v83, v84, v91, v83
	v_pk_fma_f32 v[78:79], v[26:27], v[78:79], v[30:31]
	v_fma_f32 v84, -v86, v87, 1.0
	v_fmac_f32_e32 v87, v84, v87
	v_div_scale_f32 v84, vcc, v82, v90, v82
	v_mul_f32_e32 v85, v84, v87
	v_fma_f32 v91, -v86, v85, v84
	v_fmac_f32_e32 v85, v91, v87
	v_fma_f32 v84, -v86, v85, v84
	v_div_fmas_f32 v84, v84, v87, v85
	v_div_fixup_f32 v82, v84, v90, v82
	v_cndmask_b32_e64 v86, 0, v82, s[12:13]
	v_cndmask_b32_e64 v87, 0, v83, s[12:13]
	v_mul_f32_e32 v82, 0xbfb8aa3b, v80
	v_mul_f32_e32 v83, 0xbfb8aa3b, v81
	v_exp_f32_e32 v82, v82
	v_exp_f32_e32 v83, v83
	v_pk_fma_f32 v[78:79], v[2:3], v[54:55], v[78:79]
	v_cndmask_b32_e64 v51, 0, v51, s[12:13]
; __device__ __forceinline__ unsigned pack2(float a, float b) { return (unsigned)f2bf(a) | ((unsigned)f2bf(b) << 16); }
; __device__ __forceinline__ float siluf(float x) { return x / (1.f + __expf(-x)); }
; #define UNPACK8(q, f)                                                                                   \
;   float f##0 = lo16(q.x), f##1 = hi16(q.x), f##2 = lo16(q.y), f##3 = hi16(q.y), f##4 = lo16(q.z),        \
;         f##5 = hi16(q.z), f##6 = lo16(q.w), f##7 = hi16(q.w)
; __device__ __forceinline__ void phase_ssd_conv(const Params& p, int layer) {
;     ...
;     for (int rr = 0; rr < 16; rr++) {
;       int t = tstart + rr;
;       float cur[8];
;       bool vt = t >= NPADR;
;       if (vt) {
;         u32x4 q = *(const u32x4*)(raw + (size_t)t * 2048 + cv);
;         UNPACK8(q, f);
;         cur[0] = f0; cur[1] = f1; cur[2] = f2; cur[3] = f3; cur[4] = f4; cur[5] = f5; cur[6] = f6; cur[7] = f7;
;       } else {
; #pragma unroll
;         for (int j = 0; j < 8; j++) cur[j] = 0.f;
;       }
;       float o[8];
; #pragma unroll
;       for (int j = 0; j < 8; j++) {
;         float s = bias[j] + w[0][j] * h[0][j] + w[1][j] * h[1][j] + w[2][j] * h[2][j] + w[3][j] * cur[j];
;         s = siluf(s);
;         if (cv < 1024 && !vt) s = 0.f;
;         o[j] = s;
;         h[0][j] = h[1][j]; h[1][j] = h[2][j]; h[2][j] = cur[j];
;       }
;       u32x4 r;
;       r.x = pack2(o[0], o[1]); r.y = pack2(o[2], o[3]); r.z = pack2(o[4], o[5]); r.w = pack2(o[6], o[7]);
;       *(u32x4*)(xc + (size_t)t * 2048 + cv) = r;
	v_pk_fma_f32 v[78:79], v[6:7], v[60:61], v[78:79]
	v_pk_add_f32 v[82:83], v[82:83], 1.0 op_sel_hi:[1,0]
	v_pk_fma_f32 v[78:79], v[22:23], v[58:59], v[78:79]
	v_div_scale_f32 v85, s[28:29], v82, v82, v80
	v_rcp_f32_e32 v90, v85
	v_mul_f32_e32 v84, 0xbfb8aa3b, v78
	v_exp_f32_e32 v84, v84
	v_cndmask_b32_e64 v44, 0, v44, s[12:13]
	v_fma_f32 v91, -v85, v90, 1.0
	v_fmac_f32_e32 v90, v91, v90
	v_div_scale_f32 v91, vcc, v80, v82, v80
	v_mul_f32_e32 v99, v91, v90
	v_fma_f32 v100, -v85, v99, v91
	v_fmac_f32_e32 v99, v100, v90
	v_fma_f32 v85, -v85, v99, v91
	v_div_scale_f32 v91, s[28:29], v83, v83, v81
	v_rcp_f32_e32 v100, v91
	v_div_fmas_f32 v85, v85, v90, v99
	v_div_fixup_f32 v80, v85, v82, v80
	v_mul_f32_e32 v85, 0xbfb8aa3b, v79
	v_fma_f32 v82, -v91, v100, 1.0
	v_exp_f32_e32 v85, v85
	v_fmac_f32_e32 v100, v82, v100
	v_div_scale_f32 v82, vcc, v81, v83, v81
	v_mul_f32_e32 v90, v82, v100
	v_fma_f32 v99, -v91, v90, v82
	v_fmac_f32_e32 v90, v99, v100
	v_pk_add_f32 v[84:85], v[84:85], 1.0 op_sel_hi:[1,0]
	v_fma_f32 v82, -v91, v90, v82
	v_div_scale_f32 v91, s[28:29], v85, v85, v79
	v_rcp_f32_e32 v99, v91
	v_div_fmas_f32 v82, v82, v100, v90
	v_div_fixup_f32 v81, v82, v83, v81
	v_cndmask_b32_e64 v81, 0, v81, s[12:13]
	v_fma_f32 v82, -v91, v99, 1.0
	v_fmac_f32_e32 v99, v82, v99
	v_div_scale_f32 v82, vcc, v79, v85, v79
	v_mul_f32_e32 v83, v82, v99
	v_fma_f32 v90, -v91, v83, v82
	v_fmac_f32_e32 v83, v90, v99
	v_div_scale_f32 v90, s[28:29], v84, v84, v78
	v_fma_f32 v82, -v91, v83, v82
	v_rcp_f32_e32 v91, v90
	v_div_fmas_f32 v82, v82, v99, v83
	v_div_fixup_f32 v79, v82, v85, v79
	v_cndmask_b32_e64 v80, 0, v80, s[12:13]
	v_fma_f32 v82, -v90, v91, 1.0
	v_fmac_f32_e32 v91, v82, v91
	v_div_scale_f32 v82, vcc, v78, v84, v78
	v_mul_f32_e32 v83, v82, v91
	v_fma_f32 v85, -v90, v83, v82
	v_fmac_f32_e32 v83, v85, v91
	v_fma_f32 v82, -v90, v83, v82
	v_div_fmas_f32 v82, v82, v91, v83
	v_div_fixup_f32 v78, v82, v84, v78
	v_cndmask_b32_e64 v78, 0, v78, s[12:13]
	v_cndmask_b32_e64 v79, 0, v79, s[12:13]
	v_bfe_u32 v82, v44, 16, 1
	v_bfe_u32 v83, v51, 16, 1
	v_bfe_u32 v84, v80, 16, 1
	v_bfe_u32 v85, v81, 16, 1
	v_add3_u32 v81, v81, v85, s35
	v_add3_u32 v80, v80, v84, s35
	v_add3_u32 v51, v51, v83, s35
	v_add3_u32 v44, v44, v82, s35
	v_bfe_u32 v82, v79, 16, 1
	v_bfe_u32 v83, v78, 16, 1
	v_bfe_u32 v84, v87, 16, 1
	v_bfe_u32 v85, v86, 16, 1
	s_add_u32 s26, s26, 0x4000
	v_lshrrev_b32_e32 v44, 16, v44
	v_lshrrev_b32_e32 v51, 16, v51
	v_lshrrev_b32_e32 v80, 16, v80
	v_lshrrev_b32_e32 v81, 16, v81
	v_add3_u32 v85, v86, v85, s35
	v_add3_u32 v84, v87, v84, s35
	v_add3_u32 v78, v78, v83, s35
	v_add3_u32 v79, v79, v82, s35
	v_add_co_u32_e32 v82, vcc, s37, v88
	s_addc_u32 s27, s27, 0
	v_and_or_b32 v81, v79, s30, v81
	v_and_or_b32 v80, v78, s30, v80
	v_and_or_b32 v79, v84, s30, v51
	v_and_or_b32 v78, v85, s30, v44
	v_addc_co_u32_e32 v83, vcc, 0, v89, vcc
	v_add_u32_e32 v50, 4, v50
	s_cmp_eq_u32 s26, 0x10000
	v_mov_b32_e32 v90, v92
	v_mov_b32_e32 v91, v93
	v_mov_b32_e32 v88, v52
	global_store_dwordx4 v[82:83], v[78:81], off
	s_waitcnt vmcnt(4)
	v_mov_b32_e32 v106, v122
	v_mov_b32_e32 v107, v123
	v_mov_b32_e32 v108, v124
	v_mov_b32_e32 v109, v125
	v_mov_b32_e32 v110, v126
	v_mov_b32_e32 v111, v127
	v_mov_b32_e32 v112, v128
	v_mov_b32_e32 v113, v129
	v_mov_b32_e32 v114, v130
	v_mov_b32_e32 v115, v131
	v_mov_b32_e32 v116, v132
	v_mov_b32_e32 v117, v133
	v_mov_b32_e32 v118, v134
	v_mov_b32_e32 v119, v135
	v_mov_b32_e32 v120, v136
	v_mov_b32_e32 v121, v137
	v_mov_b32_e32 v122, v138
	v_mov_b32_e32 v123, v139
	v_mov_b32_e32 v124, v140
	v_mov_b32_e32 v125, v141
	v_mov_b32_e32 v126, v142
	v_mov_b32_e32 v127, v143
	v_mov_b32_e32 v128, v144
	v_mov_b32_e32 v129, v145
	v_mov_b32_e32 v130, v146
	v_mov_b32_e32 v131, v147
	v_mov_b32_e32 v132, v148
	v_mov_b32_e32 v133, v149
	v_mov_b32_e32 v134, v150
	v_mov_b32_e32 v135, v151
	v_mov_b32_e32 v136, v152
	v_mov_b32_e32 v137, v153
	v_mov_b32_e32 v138, v154
	v_mov_b32_e32 v139, v155
	v_mov_b32_e32 v140, v156
	v_mov_b32_e32 v141, v157
	v_mov_b32_e32 v142, v158
	v_mov_b32_e32 v143, v159
	v_mov_b32_e32 v144, v160
	v_mov_b32_e32 v145, v161
	v_mov_b32_e32 v146, v162
	v_mov_b32_e32 v147, v163
	v_mov_b32_e32 v148, v164
	v_mov_b32_e32 v149, v165
	v_mov_b32_e32 v150, v166
	v_mov_b32_e32 v151, v167
	v_mov_b32_e32 v152, v168
	v_mov_b32_e32 v153, v169
	s_cbranch_scc1 .LBB0_767
.LBB0_777:
	v_cmp_lt_i32_e64 s[12:13], s34, v50
	v_mov_b32_e32 v52, 0
	v_lshl_add_u64 v[86:87], v[66:67], 0, s[26:27]
	v_mov_b32_e32 v84, 0
	v_mov_b32_e32 v85, 0
	v_mov_b32_e32 v82, 0
	v_mov_b32_e32 v83, 0
	v_mov_b32_e32 v80, 0
	v_mov_b32_e32 v81, 0
	v_mov_b32_e32 v78, 0
	v_mov_b32_e32 v79, 0
	s_and_saveexec_b64 s[28:29], s[12:13]
	s_cbranch_execz .LBB0_779
	s_waitcnt vmcnt(15)
	v_lshlrev_b32_e32 v84, 16, v106
	v_and_b32_e32 v82, 0xffff0000, v106
	v_lshlrev_b32_e32 v85, 16, v107
	v_and_b32_e32 v83, 0xffff0000, v107
	v_lshlrev_b32_e32 v80, 16, v108
	v_and_b32_e32 v78, 0xffff0000, v108
	v_lshlrev_b32_e32 v81, 16, v109
	v_and_b32_e32 v79, 0xffff0000, v109
; __device__ __forceinline__ unsigned pack2(float a, float b) { return (unsigned)f2bf(a) | ((unsigned)f2bf(b) << 16); }
; __device__ __forceinline__ float siluf(float x) { return x / (1.f + __expf(-x)); }
; #define UNPACK8(q, f)                                                                                   \
;   float f##0 = lo16(q.x), f##1 = hi16(q.x), f##2 = lo16(q.y), f##3 = hi16(q.y), f##4 = lo16(q.z),        \
;         f##5 = hi16(q.z), f##6 = lo16(q.w), f##7 = hi16(q.w)
; __device__ __forceinline__ void phase_ssd_conv(const Params& p, int layer) {
;     ...
;     for (int rr = 0; rr < 16; rr++) {
;       int t = tstart + rr;
;       float cur[8];
;       bool vt = t >= NPADR;
;       if (vt) {
;         u32x4 q = *(const u32x4*)(raw + (size_t)t * 2048 + cv);
;         UNPACK8(q, f);
;         cur[0] = f0; cur[1] = f1; cur[2] = f2; cur[3] = f3; cur[4] = f4; cur[5] = f5; cur[6] = f6; cur[7] = f7;
;       } else {
; #pragma unroll
;         for (int j = 0; j < 8; j++) cur[j] = 0.f;
;       }
;       float o[8];
; #pragma unroll
;       for (int j = 0; j < 8; j++) {
;         float s = bias[j] + w[0][j] * h[0][j] + w[1][j] * h[1][j] + w[2][j] * h[2][j] + w[3][j] * cur[j];
;         s = siluf(s);
;         if (cv < 1024 && !vt) s = 0.f;
;         o[j] = s;
;         h[0][j] = h[1][j]; h[1][j] = h[2][j]; h[2][j] = cur[j];
;       }
;       u32x4 r;
;       r.x = pack2(o[0], o[1]); r.y = pack2(o[2], o[3]); r.z = pack2(o[4], o[5]); r.w = pack2(o[6], o[7]);
;       *(u32x4*)(xc + (size_t)t * 2048 + cv) = r;
.LBB0_779:
	s_or_b64 exec, exec, s[28:29]
	v_mov_b32_e32 v89, v53
	v_pk_fma_f32 v[88:89], v[32:33], v[88:89], v[36:37]
	v_pk_fma_f32 v[68:69], v[34:35], v[68:69], v[38:39]
	v_pk_fma_f32 v[88:89], v[16:17], v[74:75], v[88:89]
	v_pk_fma_f32 v[68:69], v[18:19], v[72:73], v[68:69]
	v_pk_fma_f32 v[88:89], v[8:9], v[90:91], v[88:89]
	v_pk_fma_f32 v[68:69], v[10:11], v[76:77], v[68:69]
	v_pk_fma_f32 v[88:89], v[12:13], v[84:85], v[88:89]
	v_pk_fma_f32 v[68:69], v[14:15], v[82:83], v[68:69]
	v_mul_f32_e32 v44, 0xbfb8aa3b, v88
	v_exp_f32_e32 v92, v44
	v_mul_f32_e32 v44, 0xbfb8aa3b, v89
	v_exp_f32_e32 v93, v44
	v_mul_f32_e32 v53, 0xbfb8aa3b, v68
	v_exp_f32_e32 v100, v53
	v_pk_fma_f32 v[56:57], v[24:25], v[56:57], v[28:29]
	v_pk_add_f32 v[92:93], v[92:93], 1.0 op_sel_hi:[1,0]
	v_pk_fma_f32 v[56:57], v[0:1], v[62:63], v[56:57]
	v_div_scale_f32 v44, s[28:29], v92, v92, v88
	v_rcp_f32_e32 v51, v44
	v_pk_fma_f32 v[56:57], v[4:5], v[70:71], v[56:57]
	s_or_b64 s[12:13], s[24:25], s[12:13]
	v_pk_fma_f32 v[56:57], v[20:21], v[80:81], v[56:57]
	v_fma_f32 v53, -v44, v51, 1.0
	v_fmac_f32_e32 v51, v53, v51
	v_div_scale_f32 v53, vcc, v88, v92, v88
	v_mul_f32_e32 v99, v53, v51
	v_fma_f32 v101, -v44, v99, v53
	v_fmac_f32_e32 v99, v101, v51
	v_fma_f32 v44, -v44, v99, v53
	v_div_scale_f32 v53, s[28:29], v93, v93, v89
	v_rcp_f32_e32 v102, v53
	v_div_fmas_f32 v44, v44, v51, v99
	v_div_fixup_f32 v44, v44, v92, v88
	v_mul_f32_e32 v92, 0xbfb8aa3b, v69
	v_fma_f32 v51, -v53, v102, 1.0
	v_exp_f32_e32 v101, v92
	v_fmac_f32_e32 v102, v51, v102
	v_div_scale_f32 v51, vcc, v89, v93, v89
	v_mul_f32_e32 v88, v51, v102
	v_fma_f32 v92, -v53, v88, v51
	v_fmac_f32_e32 v88, v92, v102
	v_pk_add_f32 v[100:101], v[100:101], 1.0 op_sel_hi:[1,0]
	v_fma_f32 v51, -v53, v88, v51
	v_div_scale_f32 v53, s[28:29], v101, v101, v69
	v_rcp_f32_e32 v92, v53
	v_div_fmas_f32 v51, v51, v102, v88
	v_div_fixup_f32 v51, v51, v93, v89
	v_pk_fma_f32 v[54:55], v[26:27], v[54:55], v[30:31]
	v_fma_f32 v88, -v53, v92, 1.0
	v_fmac_f32_e32 v92, v88, v92
	v_div_scale_f32 v88, vcc, v69, v101, v69
	v_mul_f32_e32 v89, v88, v92
	v_fma_f32 v93, -v53, v89, v88
	v_fmac_f32_e32 v89, v93, v92
	v_fma_f32 v53, -v53, v89, v88
	v_div_scale_f32 v88, s[28:29], v100, v100, v68
	v_rcp_f32_e32 v93, v88
	v_div_fmas_f32 v53, v53, v92, v89
	v_div_fixup_f32 v53, v53, v101, v69
	v_pk_fma_f32 v[54:55], v[2:3], v[60:61], v[54:55]
	v_fma_f32 v69, -v88, v93, 1.0
	v_fmac_f32_e32 v93, v69, v93
	v_div_scale_f32 v69, vcc, v68, v100, v68
	v_mul_f32_e32 v89, v69, v93
	v_fma_f32 v92, -v88, v89, v69
	v_fmac_f32_e32 v89, v92, v93
	v_fma_f32 v69, -v88, v89, v69
	v_div_fmas_f32 v69, v69, v93, v89
	v_div_fixup_f32 v68, v69, v100, v68
	v_cndmask_b32_e64 v92, 0, v68, s[12:13]
	v_mul_f32_e32 v68, 0xbfb8aa3b, v56
	v_mul_f32_e32 v69, 0xbfb8aa3b, v57
	v_exp_f32_e32 v68, v68
	v_exp_f32_e32 v69, v69
	v_pk_fma_f32 v[54:55], v[6:7], v[58:59], v[54:55]
	v_cndmask_b32_e64 v51, 0, v51, s[12:13]
	v_pk_fma_f32 v[54:55], v[22:23], v[78:79], v[54:55]
	v_pk_add_f32 v[68:69], v[68:69], 1.0 op_sel_hi:[1,0]
	v_mul_f32_e32 v88, 0xbfb8aa3b, v54
	v_div_scale_f32 v89, s[28:29], v68, v68, v56
	v_rcp_f32_e32 v93, v89
	v_exp_f32_e32 v88, v88
	v_cndmask_b32_e64 v44, 0, v44, s[12:13]
	v_cndmask_b32_e64 v53, 0, v53, s[12:13]
	v_fma_f32 v99, -v89, v93, 1.0
	v_fmac_f32_e32 v93, v99, v93
	v_div_scale_f32 v99, vcc, v56, v68, v56
	v_mul_f32_e32 v100, v99, v93
	v_fma_f32 v101, -v89, v100, v99
	v_fmac_f32_e32 v100, v101, v93
	v_fma_f32 v89, -v89, v100, v99
	v_div_scale_f32 v99, s[28:29], v69, v69, v57
	v_rcp_f32_e32 v101, v99
	v_div_fmas_f32 v89, v89, v93, v100
	v_div_fixup_f32 v56, v89, v68, v56
	v_mul_f32_e32 v89, 0xbfb8aa3b, v55
	v_fma_f32 v68, -v99, v101, 1.0
	v_exp_f32_e32 v89, v89
	v_fmac_f32_e32 v101, v68, v101
	v_div_scale_f32 v68, vcc, v57, v69, v57
	v_mul_f32_e32 v93, v68, v101
	v_fma_f32 v100, -v99, v93, v68
	v_fmac_f32_e32 v93, v100, v101
	v_pk_add_f32 v[88:89], v[88:89], 1.0 op_sel_hi:[1,0]
	v_fma_f32 v68, -v99, v93, v68
	v_div_scale_f32 v99, s[28:29], v89, v89, v55
	v_rcp_f32_e32 v100, v99
	v_div_fmas_f32 v68, v68, v101, v93
	v_div_fixup_f32 v57, v68, v69, v57
	v_cndmask_b32_e64 v57, 0, v57, s[12:13]
	v_fma_f32 v68, -v99, v100, 1.0
	v_fmac_f32_e32 v100, v68, v100
	v_div_scale_f32 v68, vcc, v55, v89, v55
	v_mul_f32_e32 v69, v68, v100
	v_fma_f32 v93, -v99, v69, v68
	v_fmac_f32_e32 v69, v93, v100
	v_div_scale_f32 v93, s[28:29], v88, v88, v54
	v_fma_f32 v68, -v99, v69, v68
	v_rcp_f32_e32 v99, v93
	v_div_fmas_f32 v68, v68, v100, v69
	v_div_fixup_f32 v55, v68, v89, v55
	v_cndmask_b32_e64 v56, 0, v56, s[12:13]
	v_fma_f32 v68, -v93, v99, 1.0
	v_fmac_f32_e32 v99, v68, v99
	v_div_scale_f32 v68, vcc, v54, v88, v54
	v_mul_f32_e32 v69, v68, v99
	v_fma_f32 v89, -v93, v69, v68
	v_fmac_f32_e32 v69, v89, v99
	v_fma_f32 v68, -v93, v69, v68
	v_div_fmas_f32 v68, v68, v99, v69
	v_div_fixup_f32 v54, v68, v88, v54
	v_cndmask_b32_e64 v54, 0, v54, s[12:13]
	v_bfe_u32 v68, v44, 16, 1
	v_bfe_u32 v69, v51, 16, 1
	v_bfe_u32 v88, v56, 16, 1
	v_bfe_u32 v89, v57, 16, 1
	v_add3_u32 v57, v57, v89, s35
	v_add3_u32 v56, v56, v88, s35
	v_add3_u32 v51, v51, v69, s35
	v_add3_u32 v44, v44, v68, s35
	v_bfe_u32 v69, v54, 16, 1
	v_bfe_u32 v89, v92, 16, 1
	v_cndmask_b32_e64 v55, 0, v55, s[12:13]
	v_lshrrev_b32_e32 v44, 16, v44
	v_lshrrev_b32_e32 v56, 16, v56
	v_bfe_u32 v88, v53, 16, 1
	v_add3_u32 v89, v92, v89, s35
	v_add3_u32 v54, v54, v69, s35
	v_bfe_u32 v68, v55, 16, 1
	v_add3_u32 v53, v53, v88, s35
	v_and_or_b32 v56, v54, s30, v56
	v_and_or_b32 v54, v89, s30, v44
	v_lshl_add_u64 v[88:89], v[64:65], 0, s[26:27]
	v_lshrrev_b32_e32 v51, 16, v51
	v_lshrrev_b32_e32 v57, 16, v57
	v_add3_u32 v55, v55, v68, s35
	v_add_co_u32_e32 v68, vcc, 0x15f00000, v88
	v_and_or_b32 v57, v55, s30, v57
	v_and_or_b32 v55, v53, s30, v51
	v_addc_co_u32_e32 v69, vcc, 0, v89, vcc
	global_store_dwordx4 v[68:69], v[54:57], off
	v_cmp_lt_i32_e64 s[12:13], s36, v50
	v_mov_b32_e32 v53, 0
	v_mov_b32_e32 v68, 0
	v_mov_b32_e32 v69, 0
	v_mov_b32_e32 v56, 0
	v_mov_b32_e32 v57, 0
	v_mov_b32_e32 v54, 0
	v_mov_b32_e32 v55, 0
	s_and_saveexec_b64 s[28:29], s[12:13]
	s_cbranch_execz .LBB0_781
	s_waitcnt vmcnt(15)
	v_lshlrev_b32_e32 v52, 16, v110
	v_and_b32_e32 v68, 0xffff0000, v110
	v_lshlrev_b32_e32 v53, 16, v111
	v_and_b32_e32 v69, 0xffff0000, v111
	v_lshlrev_b32_e32 v56, 16, v112
	v_and_b32_e32 v54, 0xffff0000, v112
	v_lshlrev_b32_e32 v57, 16, v113
	v_and_b32_e32 v55, 0xffff0000, v113
; __device__ __forceinline__ unsigned pack2(float a, float b) { return (unsigned)f2bf(a) | ((unsigned)f2bf(b) << 16); }
; __device__ __forceinline__ float siluf(float x) { return x / (1.f + __expf(-x)); }
; #define UNPACK8(q, f)                                                                                   \
;   float f##0 = lo16(q.x), f##1 = hi16(q.x), f##2 = lo16(q.y), f##3 = hi16(q.y), f##4 = lo16(q.z),        \
;         f##5 = hi16(q.z), f##6 = lo16(q.w), f##7 = hi16(q.w)
; __device__ __forceinline__ void phase_ssd_conv(const Params& p, int layer) {
;     ...
;     for (int rr = 0; rr < 16; rr++) {
;       int t = tstart + rr;
;       float cur[8];
;       bool vt = t >= NPADR;
;       if (vt) {
;         u32x4 q = *(const u32x4*)(raw + (size_t)t * 2048 + cv);
;         UNPACK8(q, f);
;         cur[0] = f0; cur[1] = f1; cur[2] = f2; cur[3] = f3; cur[4] = f4; cur[5] = f5; cur[6] = f6; cur[7] = f7;
;       } else {
; #pragma unroll
;         for (int j = 0; j < 8; j++) cur[j] = 0.f;
;       }
;       float o[8];
; #pragma unroll
;       for (int j = 0; j < 8; j++) {
;         float s = bias[j] + w[0][j] * h[0][j] + w[1][j] * h[1][j] + w[2][j] * h[2][j] + w[3][j] * cur[j];
;         s = siluf(s);
;         if (cv < 1024 && !vt) s = 0.f;
;         o[j] = s;
;         h[0][j] = h[1][j]; h[1][j] = h[2][j]; h[2][j] = cur[j];
;       }
;       u32x4 r;
;       r.x = pack2(o[0], o[1]); r.y = pack2(o[2], o[3]); r.z = pack2(o[4], o[5]); r.w = pack2(o[6], o[7]);
;       *(u32x4*)(xc + (size_t)t * 2048 + cv) = r;
.LBB0_781:
	s_or_b64 exec, exec, s[28:29]
	v_pk_fma_f32 v[74:75], v[32:33], v[74:75], v[36:37]
	v_pk_fma_f32 v[72:73], v[34:35], v[72:73], v[38:39]
	v_pk_fma_f32 v[74:75], v[16:17], v[90:91], v[74:75]
	v_pk_fma_f32 v[72:73], v[18:19], v[76:77], v[72:73]
	v_pk_fma_f32 v[74:75], v[8:9], v[84:85], v[74:75]
	v_pk_fma_f32 v[72:73], v[10:11], v[82:83], v[72:73]
	v_pk_fma_f32 v[74:75], v[12:13], v[52:53], v[74:75]
	v_pk_fma_f32 v[72:73], v[14:15], v[68:69], v[72:73]
	v_mul_f32_e32 v44, 0xbfb8aa3b, v74
	v_exp_f32_e32 v92, v44
	v_mul_f32_e32 v44, 0xbfb8aa3b, v75
	v_exp_f32_e32 v93, v44
	v_mul_f32_e32 v99, 0xbfb8aa3b, v72
	v_exp_f32_e32 v100, v99
	v_pk_fma_f32 v[62:63], v[24:25], v[62:63], v[28:29]
	v_pk_add_f32 v[92:93], v[92:93], 1.0 op_sel_hi:[1,0]
	v_pk_fma_f32 v[62:63], v[0:1], v[70:71], v[62:63]
	v_div_scale_f32 v44, s[28:29], v92, v92, v74
	v_rcp_f32_e32 v51, v44
	v_pk_fma_f32 v[62:63], v[4:5], v[80:81], v[62:63]
	s_or_b64 s[12:13], s[24:25], s[12:13]
	v_pk_fma_f32 v[62:63], v[20:21], v[56:57], v[62:63]
	v_fma_f32 v99, -v44, v51, 1.0
	v_fmac_f32_e32 v51, v99, v51
	v_div_scale_f32 v99, vcc, v74, v92, v74
	v_mul_f32_e32 v101, v99, v51
	v_fma_f32 v102, -v44, v101, v99
	v_fmac_f32_e32 v101, v102, v51
	v_fma_f32 v44, -v44, v101, v99
	v_div_scale_f32 v99, s[28:29], v93, v93, v75
	v_rcp_f32_e32 v102, v99
	v_div_fmas_f32 v44, v44, v51, v101
	v_div_fixup_f32 v44, v44, v92, v74
	v_mul_f32_e32 v92, 0xbfb8aa3b, v73
	v_exp_f32_e32 v101, v92
	v_fma_f32 v51, -v99, v102, 1.0
	v_fmac_f32_e32 v102, v51, v102
	v_div_scale_f32 v51, vcc, v75, v93, v75
	v_mul_f32_e32 v74, v51, v102
	v_fma_f32 v92, -v99, v74, v51
	v_pk_add_f32 v[100:101], v[100:101], 1.0 op_sel_hi:[1,0]
	v_fmac_f32_e32 v74, v92, v102
	v_div_scale_f32 v92, s[28:29], v101, v101, v73
	v_fma_f32 v51, -v99, v74, v51
	v_rcp_f32_e32 v99, v92
	v_div_fmas_f32 v51, v51, v102, v74
	v_div_fixup_f32 v51, v51, v93, v75
	v_pk_fma_f32 v[60:61], v[26:27], v[60:61], v[30:31]
	v_fma_f32 v74, -v92, v99, 1.0
	v_fmac_f32_e32 v99, v74, v99
	v_div_scale_f32 v74, vcc, v73, v101, v73
	v_mul_f32_e32 v75, v74, v99
	v_fma_f32 v93, -v92, v75, v74
	v_fmac_f32_e32 v75, v93, v99
	v_fma_f32 v74, -v92, v75, v74
	v_div_scale_f32 v92, s[28:29], v100, v100, v72
	v_rcp_f32_e32 v93, v92
	v_div_fmas_f32 v74, v74, v99, v75
	v_div_fixup_f32 v73, v74, v101, v73
	v_pk_fma_f32 v[60:61], v[2:3], v[58:59], v[60:61]
	v_fma_f32 v74, -v92, v93, 1.0
	v_fmac_f32_e32 v93, v74, v93
	v_div_scale_f32 v74, vcc, v72, v100, v72
	v_mul_f32_e32 v75, v74, v93
	v_fma_f32 v99, -v92, v75, v74
	v_fmac_f32_e32 v75, v99, v93
	v_fma_f32 v74, -v92, v75, v74
	v_div_fmas_f32 v74, v74, v93, v75
	v_div_fixup_f32 v72, v74, v100, v72
	v_cndmask_b32_e64 v92, 0, v72, s[12:13]
	v_cndmask_b32_e64 v93, 0, v73, s[12:13]
	v_mul_f32_e32 v72, 0xbfb8aa3b, v62
	v_mul_f32_e32 v73, 0xbfb8aa3b, v63
	v_exp_f32_e32 v72, v72
	v_exp_f32_e32 v73, v73
	v_pk_fma_f32 v[60:61], v[6:7], v[78:79], v[60:61]
	v_cndmask_b32_e64 v51, 0, v51, s[12:13]
	v_pk_fma_f32 v[60:61], v[22:23], v[54:55], v[60:61]
	v_pk_add_f32 v[72:73], v[72:73], 1.0 op_sel_hi:[1,0]
	v_mul_f32_e32 v74, 0xbfb8aa3b, v60
	v_div_scale_f32 v75, s[28:29], v72, v72, v62
	v_rcp_f32_e32 v99, v75
	v_exp_f32_e32 v74, v74
	v_cndmask_b32_e64 v44, 0, v44, s[12:13]
	v_fma_f32 v100, -v75, v99, 1.0
	v_fmac_f32_e32 v99, v100, v99
	v_div_scale_f32 v100, vcc, v62, v72, v62
	v_mul_f32_e32 v101, v100, v99
	v_fma_f32 v102, -v75, v101, v100
	v_fmac_f32_e32 v101, v102, v99
	v_fma_f32 v75, -v75, v101, v100
	v_div_scale_f32 v100, s[28:29], v73, v73, v63
	v_rcp_f32_e32 v102, v100
	v_div_fmas_f32 v75, v75, v99, v101
	v_div_fixup_f32 v62, v75, v72, v62
	v_mul_f32_e32 v75, 0xbfb8aa3b, v61
	v_fma_f32 v72, -v100, v102, 1.0
	v_exp_f32_e32 v75, v75
	v_fmac_f32_e32 v102, v72, v102
	v_div_scale_f32 v72, vcc, v63, v73, v63
	v_mul_f32_e32 v99, v72, v102
	v_fma_f32 v101, -v100, v99, v72
	v_fmac_f32_e32 v99, v101, v102
	v_pk_add_f32 v[74:75], v[74:75], 1.0 op_sel_hi:[1,0]
	v_fma_f32 v72, -v100, v99, v72
	v_div_scale_f32 v100, s[28:29], v75, v75, v61
	v_rcp_f32_e32 v101, v100
	v_div_fmas_f32 v72, v72, v102, v99
	v_div_fixup_f32 v63, v72, v73, v63
	v_cndmask_b32_e64 v63, 0, v63, s[12:13]
	v_fma_f32 v72, -v100, v101, 1.0
	v_fmac_f32_e32 v101, v72, v101
	v_div_scale_f32 v72, vcc, v61, v75, v61
	v_mul_f32_e32 v73, v72, v101
	v_fma_f32 v99, -v100, v73, v72
	v_fmac_f32_e32 v73, v99, v101
	v_div_scale_f32 v99, s[28:29], v74, v74, v60
	v_fma_f32 v72, -v100, v73, v72
	v_rcp_f32_e32 v100, v99
	v_div_fmas_f32 v72, v72, v101, v73
	v_div_fixup_f32 v61, v72, v75, v61
	v_cndmask_b32_e64 v62, 0, v62, s[12:13]
	v_fma_f32 v72, -v99, v100, 1.0
	v_fmac_f32_e32 v100, v72, v100
	v_div_scale_f32 v72, vcc, v60, v74, v60
	v_mul_f32_e32 v73, v72, v100
	v_fma_f32 v75, -v99, v73, v72
	v_fmac_f32_e32 v73, v75, v100
	v_fma_f32 v72, -v99, v73, v72
	v_div_fmas_f32 v72, v72, v100, v73
	v_div_fixup_f32 v60, v72, v74, v60
	v_cndmask_b32_e64 v60, 0, v60, s[12:13]
	v_cndmask_b32_e64 v61, 0, v61, s[12:13]
	v_bfe_u32 v72, v44, 16, 1
	v_bfe_u32 v73, v51, 16, 1
	v_bfe_u32 v74, v62, 16, 1
	v_bfe_u32 v75, v63, 16, 1
	v_add3_u32 v63, v63, v75, s35
	v_add3_u32 v62, v62, v74, s35
	v_add3_u32 v51, v51, v73, s35
	v_add3_u32 v44, v44, v72, s35
	v_bfe_u32 v72, v61, 16, 1
	v_bfe_u32 v73, v60, 16, 1
	v_bfe_u32 v74, v93, 16, 1
	v_bfe_u32 v75, v92, 16, 1
	v_lshrrev_b32_e32 v44, 16, v44
	v_lshrrev_b32_e32 v51, 16, v51
	v_lshrrev_b32_e32 v62, 16, v62
	v_lshrrev_b32_e32 v63, 16, v63
	v_add3_u32 v75, v92, v75, s35
	v_add3_u32 v74, v93, v74, s35
	v_add3_u32 v60, v60, v73, s35
	v_add3_u32 v61, v61, v72, s35
	v_add_co_u32_e32 v72, vcc, 0x15f01000, v88
	v_and_or_b32 v63, v61, s30, v63
	v_and_or_b32 v62, v60, s30, v62
	v_and_or_b32 v61, v74, s30, v51
	v_and_or_b32 v60, v75, s30, v44
	v_addc_co_u32_e32 v73, vcc, 0, v89, vcc
	v_add_u32_e32 v44, 2, v50
	global_store_dwordx4 v[72:73], v[60:63], off
	v_cmp_lt_i32_e64 s[12:13], s34, v44
	v_mov_b32_e32 v92, 0
	v_mov_b32_e32 v74, 0
	v_mov_b32_e32 v75, 0
	v_mov_b32_e32 v72, 0
	v_mov_b32_e32 v73, 0
	v_mov_b32_e32 v62, 0
	v_mov_b32_e32 v63, 0
	v_mov_b32_e32 v60, 0
	v_mov_b32_e32 v61, 0
	s_and_saveexec_b64 s[28:29], s[12:13]
	s_cbranch_execz .LBB0_783
	s_waitcnt vmcnt(15)
	v_lshlrev_b32_e32 v74, 16, v114
	v_and_b32_e32 v72, 0xffff0000, v114
	v_lshlrev_b32_e32 v75, 16, v115
	v_and_b32_e32 v73, 0xffff0000, v115
	v_lshlrev_b32_e32 v62, 16, v116
	v_and_b32_e32 v60, 0xffff0000, v116
	v_lshlrev_b32_e32 v63, 16, v117
	v_and_b32_e32 v61, 0xffff0000, v117
; __device__ __forceinline__ unsigned pack2(float a, float b) { return (unsigned)f2bf(a) | ((unsigned)f2bf(b) << 16); }
; __device__ __forceinline__ float siluf(float x) { return x / (1.f + __expf(-x)); }
; #define UNPACK8(q, f)                                                                                   \
;   float f##0 = lo16(q.x), f##1 = hi16(q.x), f##2 = lo16(q.y), f##3 = hi16(q.y), f##4 = lo16(q.z),        \
;         f##5 = hi16(q.z), f##6 = lo16(q.w), f##7 = hi16(q.w)
; __device__ __forceinline__ void phase_ssd_conv(const Params& p, int layer) {
;     ...
;     for (int rr = 0; rr < 16; rr++) {
;       int t = tstart + rr;
;       float cur[8];
;       bool vt = t >= NPADR;
;       if (vt) {
;         u32x4 q = *(const u32x4*)(raw + (size_t)t * 2048 + cv);
;         UNPACK8(q, f);
;         cur[0] = f0; cur[1] = f1; cur[2] = f2; cur[3] = f3; cur[4] = f4; cur[5] = f5; cur[6] = f6; cur[7] = f7;
;       } else {
; #pragma unroll
;         for (int j = 0; j < 8; j++) cur[j] = 0.f;
;       }
;       float o[8];
; #pragma unroll
;       for (int j = 0; j < 8; j++) {
;         float s = bias[j] + w[0][j] * h[0][j] + w[1][j] * h[1][j] + w[2][j] * h[2][j] + w[3][j] * cur[j];
;         s = siluf(s);
;         if (cv < 1024 && !vt) s = 0.f;
;         o[j] = s;
;         h[0][j] = h[1][j]; h[1][j] = h[2][j]; h[2][j] = cur[j];
;       }
;       u32x4 r;
;       r.x = pack2(o[0], o[1]); r.y = pack2(o[2], o[3]); r.z = pack2(o[4], o[5]); r.w = pack2(o[6], o[7]);
;       *(u32x4*)(xc + (size_t)t * 2048 + cv) = r;
.LBB0_783:
	s_or_b64 exec, exec, s[28:29]
	v_pk_fma_f32 v[90:91], v[32:33], v[90:91], v[36:37]
	v_pk_fma_f32 v[76:77], v[34:35], v[76:77], v[38:39]
	v_pk_fma_f32 v[90:91], v[16:17], v[84:85], v[90:91]
	v_pk_fma_f32 v[76:77], v[18:19], v[82:83], v[76:77]
	v_pk_fma_f32 v[90:91], v[8:9], v[52:53], v[90:91]
	v_pk_fma_f32 v[76:77], v[10:11], v[68:69], v[76:77]
	v_pk_fma_f32 v[90:91], v[12:13], v[74:75], v[90:91]
	v_pk_fma_f32 v[76:77], v[14:15], v[72:73], v[76:77]
	v_mul_f32_e32 v44, 0xbfb8aa3b, v90
	v_exp_f32_e32 v100, v44
	v_mul_f32_e32 v44, 0xbfb8aa3b, v91
	v_exp_f32_e32 v101, v44
	v_mul_f32_e32 v93, 0xbfb8aa3b, v76
	v_exp_f32_e32 v102, v93
	v_pk_fma_f32 v[70:71], v[24:25], v[70:71], v[28:29]
	v_pk_add_f32 v[100:101], v[100:101], 1.0 op_sel_hi:[1,0]
	v_pk_fma_f32 v[70:71], v[0:1], v[80:81], v[70:71]
	v_div_scale_f32 v44, s[28:29], v100, v100, v90
	v_rcp_f32_e32 v51, v44
	v_pk_fma_f32 v[70:71], v[4:5], v[56:57], v[70:71]
	s_or_b64 s[12:13], s[24:25], s[12:13]
	v_pk_fma_f32 v[70:71], v[20:21], v[62:63], v[70:71]
	v_fma_f32 v93, -v44, v51, 1.0
	v_fmac_f32_e32 v51, v93, v51
	v_div_scale_f32 v93, vcc, v90, v100, v90
	v_mul_f32_e32 v99, v93, v51
	v_fma_f32 v103, -v44, v99, v93
	v_fmac_f32_e32 v99, v103, v51
	v_fma_f32 v44, -v44, v99, v93
	v_div_scale_f32 v93, s[28:29], v101, v101, v91
	v_rcp_f32_e32 v104, v93
	v_div_fmas_f32 v44, v44, v51, v99
	v_mul_f32_e32 v99, 0xbfb8aa3b, v77
	v_exp_f32_e32 v103, v99
	v_fma_f32 v51, -v93, v104, 1.0
	v_fmac_f32_e32 v104, v51, v104
	v_div_scale_f32 v51, vcc, v91, v101, v91
	v_div_fixup_f32 v44, v44, v100, v90
	v_mul_f32_e32 v90, v51, v104
	v_fma_f32 v99, -v93, v90, v51
	v_fmac_f32_e32 v90, v99, v104
	v_pk_add_f32 v[102:103], v[102:103], 1.0 op_sel_hi:[1,0]
	v_fma_f32 v51, -v93, v90, v51
	v_div_scale_f32 v93, s[28:29], v103, v103, v77
	v_rcp_f32_e32 v99, v93
	v_div_fmas_f32 v51, v51, v104, v90
	v_div_fixup_f32 v51, v51, v101, v91
	v_pk_fma_f32 v[58:59], v[26:27], v[58:59], v[30:31]
	v_fma_f32 v90, -v93, v99, 1.0
	v_fmac_f32_e32 v99, v90, v99
	v_div_scale_f32 v90, vcc, v77, v103, v77
	v_mul_f32_e32 v91, v90, v99
	v_fma_f32 v100, -v93, v91, v90
	v_fmac_f32_e32 v91, v100, v99
	v_fma_f32 v90, -v93, v91, v90
	v_div_scale_f32 v93, s[28:29], v102, v102, v76
	v_rcp_f32_e32 v100, v93
	v_div_fmas_f32 v90, v90, v99, v91
	v_div_fixup_f32 v77, v90, v103, v77
	v_pk_fma_f32 v[58:59], v[2:3], v[78:79], v[58:59]
	v_fma_f32 v90, -v93, v100, 1.0
	v_fmac_f32_e32 v100, v90, v100
	v_div_scale_f32 v90, vcc, v76, v102, v76
	v_mul_f32_e32 v91, v90, v100
	v_fma_f32 v99, -v93, v91, v90
	v_fmac_f32_e32 v91, v99, v100
	v_fma_f32 v90, -v93, v91, v90
	v_div_fmas_f32 v90, v90, v100, v91
	v_div_fixup_f32 v76, v90, v102, v76
	v_cndmask_b32_e64 v93, 0, v76, s[12:13]
	v_cndmask_b32_e64 v99, 0, v77, s[12:13]
	v_mul_f32_e32 v76, 0xbfb8aa3b, v70
	v_mul_f32_e32 v77, 0xbfb8aa3b, v71
	v_exp_f32_e32 v76, v76
	v_exp_f32_e32 v77, v77
	v_pk_fma_f32 v[58:59], v[6:7], v[54:55], v[58:59]
	v_cndmask_b32_e64 v51, 0, v51, s[12:13]
	v_pk_fma_f32 v[58:59], v[22:23], v[60:61], v[58:59]
	v_pk_add_f32 v[76:77], v[76:77], 1.0 op_sel_hi:[1,0]
	v_mul_f32_e32 v90, 0xbfb8aa3b, v58
	v_div_scale_f32 v91, s[28:29], v76, v76, v70
	v_rcp_f32_e32 v100, v91
	v_exp_f32_e32 v90, v90
	v_cndmask_b32_e64 v44, 0, v44, s[12:13]
	v_fma_f32 v101, -v91, v100, 1.0
	v_fmac_f32_e32 v100, v101, v100
	v_div_scale_f32 v101, vcc, v70, v76, v70
	v_mul_f32_e32 v102, v101, v100
	v_fma_f32 v103, -v91, v102, v101
	v_fmac_f32_e32 v102, v103, v100
	v_fma_f32 v91, -v91, v102, v101
	v_div_scale_f32 v101, s[28:29], v77, v77, v71
	v_rcp_f32_e32 v103, v101
	v_div_fmas_f32 v91, v91, v100, v102
	v_div_fixup_f32 v70, v91, v76, v70
	v_mul_f32_e32 v91, 0xbfb8aa3b, v59
	v_fma_f32 v76, -v101, v103, 1.0
	v_exp_f32_e32 v91, v91
	v_fmac_f32_e32 v103, v76, v103
	v_div_scale_f32 v76, vcc, v71, v77, v71
	v_mul_f32_e32 v100, v76, v103
	v_fma_f32 v102, -v101, v100, v76
	v_fmac_f32_e32 v100, v102, v103
	v_pk_add_f32 v[90:91], v[90:91], 1.0 op_sel_hi:[1,0]
	v_fma_f32 v76, -v101, v100, v76
	v_div_scale_f32 v101, s[28:29], v91, v91, v59
	v_rcp_f32_e32 v102, v101
	v_div_fmas_f32 v76, v76, v103, v100
	v_div_fixup_f32 v71, v76, v77, v71
	v_cndmask_b32_e64 v70, 0, v70, s[12:13]
	v_fma_f32 v76, -v101, v102, 1.0
	v_fmac_f32_e32 v102, v76, v102
	v_div_scale_f32 v76, vcc, v59, v91, v59
	v_mul_f32_e32 v77, v76, v102
	v_fma_f32 v100, -v101, v77, v76
	v_fmac_f32_e32 v77, v100, v102
	v_div_scale_f32 v100, s[28:29], v90, v90, v58
	v_fma_f32 v76, -v101, v77, v76
	v_rcp_f32_e32 v101, v100
	v_div_fmas_f32 v76, v76, v102, v77
	v_div_fixup_f32 v59, v76, v91, v59
	v_cndmask_b32_e64 v71, 0, v71, s[12:13]
	v_fma_f32 v76, -v100, v101, 1.0
	v_fmac_f32_e32 v101, v76, v101
	v_div_scale_f32 v76, vcc, v58, v90, v58
	v_mul_f32_e32 v77, v76, v101
	v_fma_f32 v91, -v100, v77, v76
	v_fmac_f32_e32 v77, v91, v101
	v_fma_f32 v76, -v100, v77, v76
	v_div_fmas_f32 v76, v76, v101, v77
	v_div_fixup_f32 v58, v76, v90, v58
	v_cndmask_b32_e64 v58, 0, v58, s[12:13]
	v_bfe_u32 v77, v51, 16, 1
	v_bfe_u32 v90, v70, 16, 1
	v_cndmask_b32_e64 v59, 0, v59, s[12:13]
	v_bfe_u32 v76, v44, 16, 1
	v_bfe_u32 v91, v71, 16, 1
	v_add3_u32 v70, v70, v90, s35
	v_add3_u32 v51, v51, v77, s35
	v_bfe_u32 v77, v58, 16, 1
	v_add3_u32 v71, v71, v91, s35
	v_add3_u32 v44, v44, v76, s35
	v_lshrrev_b32_e32 v70, 16, v70
	v_bfe_u32 v76, v59, 16, 1
	v_bfe_u32 v90, v99, 16, 1
	v_bfe_u32 v91, v93, 16, 1
	v_add3_u32 v58, v58, v77, s35
	v_lshrrev_b32_e32 v44, 16, v44
	v_lshrrev_b32_e32 v51, 16, v51
	v_lshrrev_b32_e32 v71, 16, v71
	v_add3_u32 v91, v93, v91, s35
	v_add3_u32 v90, v99, v90, s35
	v_add3_u32 v59, v59, v76, s35
	v_and_or_b32 v102, v58, s30, v70
	v_add_co_u32_e32 v58, vcc, 0x15f02000, v88
	v_and_or_b32 v103, v59, s30, v71
	v_and_or_b32 v101, v90, s30, v51
	v_and_or_b32 v100, v91, s30, v44
	v_addc_co_u32_e32 v59, vcc, 0, v89, vcc
	v_add_u32_e32 v44, 3, v50
	global_store_dwordx4 v[58:59], v[100:103], off
	v_cmp_lt_i32_e64 s[12:13], s34, v44
	v_mov_b32_e32 v93, 0
	v_mov_b32_e32 v76, 0
	v_mov_b32_e32 v77, 0
	v_mov_b32_e32 v70, 0
	v_mov_b32_e32 v71, 0
	v_mov_b32_e32 v58, 0
	v_mov_b32_e32 v59, 0
	s_and_saveexec_b64 s[28:29], s[12:13]
	s_cbranch_execz .LBB0_776
	s_waitcnt vmcnt(15)
	v_lshlrev_b32_e32 v92, 16, v118
	v_and_b32_e32 v76, 0xffff0000, v118
	v_lshlrev_b32_e32 v93, 16, v119
	v_and_b32_e32 v77, 0xffff0000, v119
	v_lshlrev_b32_e32 v70, 16, v120
	v_and_b32_e32 v58, 0xffff0000, v120
	v_lshlrev_b32_e32 v71, 16, v121
	v_and_b32_e32 v59, 0xffff0000, v121
	s_branch .LBB0_776

; __device__ __forceinline__ unsigned pack2(float a, float b) { return (unsigned)f2bf(a) | ((unsigned)f2bf(b) << 16); }
; __device__ __forceinline__ float siluf(float x) { return x / (1.f + __expf(-x)); }
; #define UNPACK8(q, f)                                                                                   \
;   float f##0 = lo16(q.x), f##1 = hi16(q.x), f##2 = lo16(q.y), f##3 = hi16(q.y), f##4 = lo16(q.z),        \
;         f##5 = hi16(q.z), f##6 = lo16(q.w), f##7 = hi16(q.w)
; __device__ __forceinline__ void phase_ssd_conv(const Params& p, int layer) {
;     ...
;     float h[3][8];
;     int tstart = c * 128 + rg * 16;
; #pragma unroll
;     for (int i = 0; i < 3; i++) {
;       int tt = tstart - 3 + i;
;       if (tt >= NPADR) {
;         u32x4 q = *(const u32x4*)(raw + (size_t)tt * 2048 + cv);
;         UNPACK8(q, f);
;         h[i][0] = f0; h[i][1] = f1; h[i][2] = f2; h[i][3] = f3; h[i][4] = f4; h[i][5] = f5; h[i][6] = f6; h[i][7] = f7;
;       } else {
; #pragma unroll
;         for (int j = 0; j < 8; j++) h[i][j] = 0.f;
;       }
;     }
; #pragma unroll 4
;     for (int rr = 0; rr < 16; rr++) {
;       int t = tstart + rr;
;       float cur[8];
;       bool vt = t >= NPADR;
;       if (vt) {
;         u32x4 q = *(const u32x4*)(raw + (size_t)t * 2048 + cv);
;         UNPACK8(q, f);
;         cur[0] = f0; cur[1] = f1; cur[2] = f2; cur[3] = f3; cur[4] = f4; cur[5] = f5; cur[6] = f6; cur[7] = f7;
;       } else {
; #pragma unroll
;         for (int j = 0; j < 8; j++) cur[j] = 0.f;
;       }
;       float o[8];
; #pragma unroll
;       for (int j = 0; j < 8; j++) {
;         float s = bias[j] + w[0][j] * h[0][j] + w[1][j] * h[1][j] + w[2][j] * h[2][j] + w[3][j] * cur[j];
;         s = siluf(s);
;         if (cv < 1024 && !vt) s = 0.f;
;         o[j] = s;
;         h[0][j] = h[1][j]; h[1][j] = h[2][j]; h[2][j] = cur[j];
;       }
;       u32x4 r;
;       r.x = pack2(o[0], o[1]); r.y = pack2(o[2], o[3]); r.z = pack2(o[4], o[5]); r.w = pack2(o[6], o[7]);
;       *(u32x4*)(xc + (size_t)t * 2048 + cv) = r;
.LBB0_3283:
	s_or_b64 exec, exec, s[12:13]
	s_and_b32 s12, s51, 7
	s_cmp_gt_u32 s25, 3
	s_waitcnt vmcnt(8)
	v_mov_b32_e32 v51, v6
	v_mov_b32_e32 v6, v2
	s_waitcnt vmcnt(7)
	v_mov_b32_e32 v2, v9
	s_waitcnt vmcnt(3)
	v_mov_b32_e32 v9, v25
	s_waitcnt vmcnt(2)
	v_mov_b32_e32 v64, v29
	v_mov_b32_e32 v29, v21
	s_waitcnt vmcnt(1)
	v_mov_b32_e32 v65, v33
	s_waitcnt vmcnt(0)
	v_mov_b32_e32 v33, v37
	s_cselect_b64 s[28:29], -1, 0
	s_ashr_i32 s27, s26, 31
	v_mov_b32_e32 v9, v10
	v_mov_b32_e32 v33, v34
	v_mov_b32_e32 v29, v30
	v_mov_b32_e32 v10, v2
	v_mov_b32_e32 v34, v65
	v_mov_b32_e32 v30, v64
	v_mov_b32_e32 v2, v1
	v_mov_b32_e32 v1, v6
	v_mov_b32_e32 v6, v5
	v_mov_b32_e32 v5, v51
	v_lshl_add_u64 v[64:65], v[40:41], 0, s[26:27]
	v_mov_b32_e32 v51, v45
	v_lshl_or_b32 v44, s12, 9, v96
	v_lshlrev_b64 v[64:65], 12, v[64:65]
	v_lshlrev_b64 v[66:67], 12, v[50:51]
	v_mov_b32_e32 v52, v13
	v_mov_b32_e32 v13, v17
	v_or_b32_e32 v64, v64, v44
	v_or_b32_e32 v66, v66, v44
	v_swap_b32 v25, v26
	v_swap_b32 v37, v38
	v_swap_b32 v17, v18
	v_swap_b32 v21, v22
	v_mov_b32_e32 v13, v14
	v_mov_b32_e32 v14, v52
	v_lshl_add_u64 v[64:65], s[66:67], 0, v[64:65]
	v_lshl_add_u64 v[66:67], s[66:67], 0, v[66:67]
	s_mov_b64 s[30:31], 0
	s_mov_b32 s99, 0
	s_mov_b32 s98, 0x11e81000
	v_lshl_add_u64 v[250:251], v[66:67], 0, s[98:99]
	global_load_dwordx4 v[106:109], v[250:251], off offset:-4096
	global_load_dwordx4 v[110:113], v[250:251], off
	s_mov_b32 s98, 0x11e83000
	v_lshl_add_u64 v[250:251], v[66:67], 0, s[98:99]
	global_load_dwordx4 v[114:117], v[250:251], off offset:-4096
	global_load_dwordx4 v[118:121], v[250:251], off
	s_mov_b32 s98, 0x11e85000
	v_lshl_add_u64 v[250:251], v[66:67], 0, s[98:99]
	global_load_dwordx4 v[122:125], v[250:251], off offset:-4096
	global_load_dwordx4 v[126:129], v[250:251], off
	s_mov_b32 s98, 0x11e87000
	v_lshl_add_u64 v[250:251], v[66:67], 0, s[98:99]
	global_load_dwordx4 v[130:133], v[250:251], off offset:-4096
	global_load_dwordx4 v[134:137], v[250:251], off
	s_mov_b32 s98, 0x11e89000
	v_lshl_add_u64 v[250:251], v[66:67], 0, s[98:99]
	global_load_dwordx4 v[138:141], v[250:251], off offset:-4096
	global_load_dwordx4 v[142:145], v[250:251], off
	s_mov_b32 s98, 0x11e8b000
	v_lshl_add_u64 v[250:251], v[66:67], 0, s[98:99]
	global_load_dwordx4 v[146:149], v[250:251], off offset:-4096
	global_load_dwordx4 v[150:153], v[250:251], off
	s_mov_b32 s98, 0x11e8d000
	v_lshl_add_u64 v[250:251], v[66:67], 0, s[98:99]
	global_load_dwordx4 v[154:157], v[250:251], off offset:-4096
	global_load_dwordx4 v[158:161], v[250:251], off
	s_mov_b32 s98, 0x11e8f000
	v_lshl_add_u64 v[250:251], v[66:67], 0, s[98:99]
	global_load_dwordx4 v[162:165], v[250:251], off offset:-4096
	global_load_dwordx4 v[166:169], v[250:251], off
	s_branch .LBB0_3285
.LBB0_3284:
	s_or_b64 exec, exec, s[34:35]
	v_pk_fma_f32 v[84:85], v[4:5], v[84:85], v[36:37]
	v_pk_fma_f32 v[82:83], v[6:7], v[82:83], v[38:39]
	v_pk_fma_f32 v[84:85], v[24:25], v[52:53], v[84:85]
	v_pk_fma_f32 v[82:83], v[26:27], v[68:69], v[82:83]
	v_pk_fma_f32 v[84:85], v[16:17], v[74:75], v[84:85]
	v_pk_fma_f32 v[82:83], v[18:19], v[72:73], v[82:83]
	v_pk_fma_f32 v[84:85], v[20:21], v[92:93], v[84:85]
	v_pk_fma_f32 v[82:83], v[22:23], v[76:77], v[82:83]
	v_mul_f32_e32 v44, 0xbfb8aa3b, v84
	v_exp_f32_e32 v86, v44
	v_mul_f32_e32 v44, 0xbfb8aa3b, v85
	v_exp_f32_e32 v87, v44
	v_mul_f32_e32 v90, 0xbfb8aa3b, v82
	v_exp_f32_e32 v90, v90
	v_pk_fma_f32 v[80:81], v[0:1], v[80:81], v[32:33]
	v_pk_add_f32 v[86:87], v[86:87], 1.0 op_sel_hi:[1,0]
	v_pk_fma_f32 v[80:81], v[8:9], v[56:57], v[80:81]
	v_div_scale_f32 v44, s[34:35], v86, v86, v84
	v_rcp_f32_e32 v51, v44
	v_pk_fma_f32 v[80:81], v[12:13], v[62:63], v[80:81]
	s_or_b64 s[12:13], s[28:29], s[12:13]
	v_pk_fma_f32 v[80:81], v[28:29], v[70:71], v[80:81]
	v_fma_f32 v91, -v44, v51, 1.0
	v_fmac_f32_e32 v51, v91, v51
	v_div_scale_f32 v91, vcc, v84, v86, v84
	v_mul_f32_e32 v99, v91, v51
	v_fma_f32 v100, -v44, v99, v91
	v_fmac_f32_e32 v99, v100, v51
	v_div_scale_f32 v100, s[34:35], v87, v87, v85
	v_fma_f32 v44, -v44, v99, v91
	v_rcp_f32_e32 v101, v100
	v_div_fmas_f32 v44, v44, v51, v99
	v_div_fixup_f32 v44, v44, v86, v84
	v_mul_f32_e32 v86, 0xbfb8aa3b, v83
	v_exp_f32_e32 v91, v86
	v_fma_f32 v51, -v100, v101, 1.0
	v_fmac_f32_e32 v101, v51, v101
	v_div_scale_f32 v51, vcc, v85, v87, v85
	v_mul_f32_e32 v84, v51, v101
	v_fma_f32 v86, -v100, v84, v51
	v_pk_add_f32 v[90:91], v[90:91], 1.0 op_sel_hi:[1,0]
	v_fmac_f32_e32 v84, v86, v101
	v_div_scale_f32 v86, s[34:35], v91, v91, v83
	v_rcp_f32_e32 v99, v86
	v_fma_f32 v51, -v100, v84, v51
	v_div_fmas_f32 v51, v51, v101, v84
	v_div_fixup_f32 v51, v51, v87, v85
	v_fma_f32 v84, -v86, v99, 1.0
	v_fmac_f32_e32 v99, v84, v99
	v_div_scale_f32 v84, vcc, v83, v91, v83
	v_mul_f32_e32 v85, v84, v99
	v_fma_f32 v87, -v86, v85, v84
	v_fmac_f32_e32 v85, v87, v99
	v_fma_f32 v84, -v86, v85, v84
	v_div_scale_f32 v86, s[34:35], v90, v90, v82
	v_rcp_f32_e32 v87, v86
	v_div_fmas_f32 v84, v84, v99, v85
	v_div_fixup_f32 v83, v84, v91, v83
	v_pk_fma_f32 v[78:79], v[2:3], v[78:79], v[34:35]
	v_fma_f32 v84, -v86, v87, 1.0
	v_fmac_f32_e32 v87, v84, v87
	v_div_scale_f32 v84, vcc, v82, v90, v82
	v_mul_f32_e32 v85, v84, v87
	v_fma_f32 v91, -v86, v85, v84
	v_fmac_f32_e32 v85, v91, v87
	v_fma_f32 v84, -v86, v85, v84
	v_div_fmas_f32 v84, v84, v87, v85
	v_div_fixup_f32 v82, v84, v90, v82
	v_cndmask_b32_e64 v86, 0, v82, s[12:13]
	v_cndmask_b32_e64 v87, 0, v83, s[12:13]
	v_mul_f32_e32 v82, 0xbfb8aa3b, v80
	v_mul_f32_e32 v83, 0xbfb8aa3b, v81
	v_exp_f32_e32 v82, v82
	v_exp_f32_e32 v83, v83
	v_pk_fma_f32 v[78:79], v[10:11], v[54:55], v[78:79]
	v_cndmask_b32_e64 v51, 0, v51, s[12:13]
; __device__ __forceinline__ unsigned pack2(float a, float b) { return (unsigned)f2bf(a) | ((unsigned)f2bf(b) << 16); }
; __device__ __forceinline__ float siluf(float x) { return x / (1.f + __expf(-x)); }
; #define UNPACK8(q, f)                                                                                   \
;   float f##0 = lo16(q.x), f##1 = hi16(q.x), f##2 = lo16(q.y), f##3 = hi16(q.y), f##4 = lo16(q.z),        \
;         f##5 = hi16(q.z), f##6 = lo16(q.w), f##7 = hi16(q.w)
; __device__ __forceinline__ void phase_ssd_conv(const Params& p, int layer) {
;     ...
;     for (int rr = 0; rr < 16; rr++) {
;       int t = tstart + rr;
;       float cur[8];
;       bool vt = t >= NPADR;
;       if (vt) {
;         u32x4 q = *(const u32x4*)(raw + (size_t)t * 2048 + cv);
;         UNPACK8(q, f);
;         cur[0] = f0; cur[1] = f1; cur[2] = f2; cur[3] = f3; cur[4] = f4; cur[5] = f5; cur[6] = f6; cur[7] = f7;
;       } else {
; #pragma unroll
;         for (int j = 0; j < 8; j++) cur[j] = 0.f;
;       }
;       float o[8];
; #pragma unroll
;       for (int j = 0; j < 8; j++) {
;         float s = bias[j] + w[0][j] * h[0][j] + w[1][j] * h[1][j] + w[2][j] * h[2][j] + w[3][j] * cur[j];
;         s = siluf(s);
;         if (cv < 1024 && !vt) s = 0.f;
;         o[j] = s;
;         h[0][j] = h[1][j]; h[1][j] = h[2][j]; h[2][j] = cur[j];
;       }
;       u32x4 r;
;       r.x = pack2(o[0], o[1]); r.y = pack2(o[2], o[3]); r.z = pack2(o[4], o[5]); r.w = pack2(o[6], o[7]);
;       *(u32x4*)(xc + (size_t)t * 2048 + cv) = r;
	v_pk_fma_f32 v[78:79], v[14:15], v[60:61], v[78:79]
	v_pk_add_f32 v[82:83], v[82:83], 1.0 op_sel_hi:[1,0]
	v_pk_fma_f32 v[78:79], v[30:31], v[58:59], v[78:79]
	v_div_scale_f32 v85, s[34:35], v82, v82, v80
	v_rcp_f32_e32 v90, v85
	v_mul_f32_e32 v84, 0xbfb8aa3b, v78
	v_exp_f32_e32 v84, v84
	v_cndmask_b32_e64 v44, 0, v44, s[12:13]
	v_fma_f32 v91, -v85, v90, 1.0
	v_fmac_f32_e32 v90, v91, v90
	v_div_scale_f32 v91, vcc, v80, v82, v80
	v_mul_f32_e32 v99, v91, v90
	v_fma_f32 v100, -v85, v99, v91
	v_fmac_f32_e32 v99, v100, v90
	v_fma_f32 v85, -v85, v99, v91
	v_div_scale_f32 v91, s[34:35], v83, v83, v81
	v_rcp_f32_e32 v100, v91
	v_div_fmas_f32 v85, v85, v90, v99
	v_div_fixup_f32 v80, v85, v82, v80
	v_mul_f32_e32 v85, 0xbfb8aa3b, v79
	v_fma_f32 v82, -v91, v100, 1.0
	v_exp_f32_e32 v85, v85
	v_fmac_f32_e32 v100, v82, v100
	v_div_scale_f32 v82, vcc, v81, v83, v81
	v_mul_f32_e32 v90, v82, v100
	v_fma_f32 v99, -v91, v90, v82
	v_fmac_f32_e32 v90, v99, v100
	v_pk_add_f32 v[84:85], v[84:85], 1.0 op_sel_hi:[1,0]
	v_fma_f32 v82, -v91, v90, v82
	v_div_scale_f32 v91, s[34:35], v85, v85, v79
	v_rcp_f32_e32 v99, v91
	v_div_fmas_f32 v82, v82, v100, v90
	v_div_fixup_f32 v81, v82, v83, v81
	v_cndmask_b32_e64 v81, 0, v81, s[12:13]
	v_fma_f32 v82, -v91, v99, 1.0
	v_fmac_f32_e32 v99, v82, v99
	v_div_scale_f32 v82, vcc, v79, v85, v79
	v_mul_f32_e32 v83, v82, v99
	v_fma_f32 v90, -v91, v83, v82
	v_fmac_f32_e32 v83, v90, v99
	v_div_scale_f32 v90, s[34:35], v84, v84, v78
	v_fma_f32 v82, -v91, v83, v82
	v_rcp_f32_e32 v91, v90
	v_div_fmas_f32 v82, v82, v99, v83
	v_div_fixup_f32 v79, v82, v85, v79
	v_cndmask_b32_e64 v80, 0, v80, s[12:13]
	v_fma_f32 v82, -v90, v91, 1.0
	v_fmac_f32_e32 v91, v82, v91
	v_div_scale_f32 v82, vcc, v78, v84, v78
	v_mul_f32_e32 v83, v82, v91
	v_fma_f32 v85, -v90, v83, v82
	v_fmac_f32_e32 v83, v85, v91
	v_fma_f32 v82, -v90, v83, v82
	v_div_fmas_f32 v82, v82, v91, v83
	v_div_fixup_f32 v78, v82, v84, v78
	v_cndmask_b32_e64 v78, 0, v78, s[12:13]
	v_cndmask_b32_e64 v79, 0, v79, s[12:13]
	v_bfe_u32 v82, v44, 16, 1
	v_bfe_u32 v83, v51, 16, 1
	v_bfe_u32 v84, v80, 16, 1
	v_bfe_u32 v85, v81, 16, 1
	v_add3_u32 v81, v81, v85, s39
	v_add3_u32 v80, v80, v84, s39
	v_add3_u32 v51, v51, v83, s39
	v_add3_u32 v44, v44, v82, s39
	v_bfe_u32 v82, v79, 16, 1
	v_bfe_u32 v83, v78, 16, 1
	v_bfe_u32 v84, v87, 16, 1
	v_bfe_u32 v85, v86, 16, 1
	s_add_u32 s30, s30, 0x4000
	v_lshrrev_b32_e32 v44, 16, v44
	v_lshrrev_b32_e32 v51, 16, v51
	v_lshrrev_b32_e32 v80, 16, v80
	v_lshrrev_b32_e32 v81, 16, v81
	v_add3_u32 v85, v86, v85, s39
	v_add3_u32 v84, v87, v84, s39
	v_add3_u32 v78, v78, v83, s39
	v_add3_u32 v79, v79, v82, s39
	v_add_co_u32_e32 v82, vcc, s41, v88
	s_addc_u32 s31, s31, 0
	v_and_or_b32 v81, v79, s33, v81
	v_and_or_b32 v80, v78, s33, v80
	v_and_or_b32 v79, v84, s33, v51
	v_and_or_b32 v78, v85, s33, v44
	v_addc_co_u32_e32 v83, vcc, 0, v89, vcc
	v_add_u32_e32 v50, 4, v50
	s_cmp_eq_u32 s30, 0x10000
	v_mov_b32_e32 v90, v92
	v_mov_b32_e32 v91, v93
	v_mov_b32_e32 v88, v52
	global_store_dwordx4 v[82:83], v[78:81], off
	s_waitcnt vmcnt(4)
	v_mov_b32_e32 v106, v122
	v_mov_b32_e32 v107, v123
	v_mov_b32_e32 v108, v124
	v_mov_b32_e32 v109, v125
	v_mov_b32_e32 v110, v126
	v_mov_b32_e32 v111, v127
	v_mov_b32_e32 v112, v128
	v_mov_b32_e32 v113, v129
	v_mov_b32_e32 v114, v130
	v_mov_b32_e32 v115, v131
	v_mov_b32_e32 v116, v132
	v_mov_b32_e32 v117, v133
	v_mov_b32_e32 v118, v134
	v_mov_b32_e32 v119, v135
	v_mov_b32_e32 v120, v136
	v_mov_b32_e32 v121, v137
	v_mov_b32_e32 v122, v138
	v_mov_b32_e32 v123, v139
	v_mov_b32_e32 v124, v140
	v_mov_b32_e32 v125, v141
	v_mov_b32_e32 v126, v142
	v_mov_b32_e32 v127, v143
	v_mov_b32_e32 v128, v144
	v_mov_b32_e32 v129, v145
	v_mov_b32_e32 v130, v146
	v_mov_b32_e32 v131, v147
	v_mov_b32_e32 v132, v148
	v_mov_b32_e32 v133, v149
	v_mov_b32_e32 v134, v150
	v_mov_b32_e32 v135, v151
	v_mov_b32_e32 v136, v152
	v_mov_b32_e32 v137, v153
	v_mov_b32_e32 v138, v154
	v_mov_b32_e32 v139, v155
	v_mov_b32_e32 v140, v156
	v_mov_b32_e32 v141, v157
	v_mov_b32_e32 v142, v158
	v_mov_b32_e32 v143, v159
	v_mov_b32_e32 v144, v160
	v_mov_b32_e32 v145, v161
	v_mov_b32_e32 v146, v162
	v_mov_b32_e32 v147, v163
	v_mov_b32_e32 v148, v164
	v_mov_b32_e32 v149, v165
	v_mov_b32_e32 v150, v166
	v_mov_b32_e32 v151, v167
	v_mov_b32_e32 v152, v168
	v_mov_b32_e32 v153, v169
	s_cbranch_scc1 .LBB0_3275
.LBB0_3285:
	v_cmp_lt_i32_e64 s[12:13], s38, v50
	v_mov_b32_e32 v52, 0
	v_lshl_add_u64 v[86:87], v[66:67], 0, s[30:31]
	v_mov_b32_e32 v84, 0
	v_mov_b32_e32 v85, 0
	v_mov_b32_e32 v82, 0
	v_mov_b32_e32 v83, 0
	v_mov_b32_e32 v80, 0
	v_mov_b32_e32 v81, 0
	v_mov_b32_e32 v78, 0
	v_mov_b32_e32 v79, 0
	s_and_saveexec_b64 s[34:35], s[12:13]
	s_cbranch_execz .LBB0_3287
	s_waitcnt vmcnt(15)
	v_lshlrev_b32_e32 v84, 16, v106
	v_and_b32_e32 v82, 0xffff0000, v106
	v_lshlrev_b32_e32 v85, 16, v107
	v_and_b32_e32 v83, 0xffff0000, v107
	v_lshlrev_b32_e32 v80, 16, v108
	v_and_b32_e32 v78, 0xffff0000, v108
	v_lshlrev_b32_e32 v81, 16, v109
	v_and_b32_e32 v79, 0xffff0000, v109
; __device__ __forceinline__ unsigned pack2(float a, float b) { return (unsigned)f2bf(a) | ((unsigned)f2bf(b) << 16); }
; __device__ __forceinline__ float siluf(float x) { return x / (1.f + __expf(-x)); }
; #define UNPACK8(q, f)                                                                                   \
;   float f##0 = lo16(q.x), f##1 = hi16(q.x), f##2 = lo16(q.y), f##3 = hi16(q.y), f##4 = lo16(q.z),        \
;         f##5 = hi16(q.z), f##6 = lo16(q.w), f##7 = hi16(q.w)
; __device__ __forceinline__ void phase_ssd_conv(const Params& p, int layer) {
;     ...
;     for (int rr = 0; rr < 16; rr++) {
;       int t = tstart + rr;
;       float cur[8];
;       bool vt = t >= NPADR;
;       if (vt) {
;         u32x4 q = *(const u32x4*)(raw + (size_t)t * 2048 + cv);
;         UNPACK8(q, f);
;         cur[0] = f0; cur[1] = f1; cur[2] = f2; cur[3] = f3; cur[4] = f4; cur[5] = f5; cur[6] = f6; cur[7] = f7;
;       } else {
; #pragma unroll
;         for (int j = 0; j < 8; j++) cur[j] = 0.f;
;       }
;       float o[8];
; #pragma unroll
;       for (int j = 0; j < 8; j++) {
;         float s = bias[j] + w[0][j] * h[0][j] + w[1][j] * h[1][j] + w[2][j] * h[2][j] + w[3][j] * cur[j];
;         s = siluf(s);
;         if (cv < 1024 && !vt) s = 0.f;
;         o[j] = s;
;         h[0][j] = h[1][j]; h[1][j] = h[2][j]; h[2][j] = cur[j];
;       }
;       u32x4 r;
;       r.x = pack2(o[0], o[1]); r.y = pack2(o[2], o[3]); r.z = pack2(o[4], o[5]); r.w = pack2(o[6], o[7]);
;       *(u32x4*)(xc + (size_t)t * 2048 + cv) = r;
.LBB0_3287:
	s_or_b64 exec, exec, s[34:35]
	v_mov_b32_e32 v89, v53
	v_pk_fma_f32 v[88:89], v[4:5], v[88:89], v[36:37]
	v_pk_fma_f32 v[68:69], v[6:7], v[68:69], v[38:39]
	v_pk_fma_f32 v[88:89], v[24:25], v[74:75], v[88:89]
	v_pk_fma_f32 v[68:69], v[26:27], v[72:73], v[68:69]
	v_pk_fma_f32 v[88:89], v[16:17], v[90:91], v[88:89]
	v_pk_fma_f32 v[68:69], v[18:19], v[76:77], v[68:69]
	v_pk_fma_f32 v[88:89], v[20:21], v[84:85], v[88:89]
	v_pk_fma_f32 v[68:69], v[22:23], v[82:83], v[68:69]
	v_mul_f32_e32 v44, 0xbfb8aa3b, v88
	v_exp_f32_e32 v92, v44
	v_mul_f32_e32 v44, 0xbfb8aa3b, v89
	v_exp_f32_e32 v93, v44
	v_mul_f32_e32 v53, 0xbfb8aa3b, v68
	v_exp_f32_e32 v100, v53
	v_pk_fma_f32 v[56:57], v[0:1], v[56:57], v[32:33]
	v_pk_add_f32 v[92:93], v[92:93], 1.0 op_sel_hi:[1,0]
	v_pk_fma_f32 v[56:57], v[8:9], v[62:63], v[56:57]
	v_div_scale_f32 v44, s[34:35], v92, v92, v88
	v_rcp_f32_e32 v51, v44
	v_pk_fma_f32 v[56:57], v[12:13], v[70:71], v[56:57]
	s_or_b64 s[12:13], s[28:29], s[12:13]
	v_pk_fma_f32 v[56:57], v[28:29], v[80:81], v[56:57]
	v_fma_f32 v53, -v44, v51, 1.0
	v_fmac_f32_e32 v51, v53, v51
	v_div_scale_f32 v53, vcc, v88, v92, v88
	v_mul_f32_e32 v99, v53, v51
	v_fma_f32 v101, -v44, v99, v53
	v_fmac_f32_e32 v99, v101, v51
	v_fma_f32 v44, -v44, v99, v53
	v_div_scale_f32 v53, s[34:35], v93, v93, v89
	v_rcp_f32_e32 v102, v53
	v_div_fmas_f32 v44, v44, v51, v99
	v_div_fixup_f32 v44, v44, v92, v88
	v_mul_f32_e32 v92, 0xbfb8aa3b, v69
	v_fma_f32 v51, -v53, v102, 1.0
	v_exp_f32_e32 v101, v92
	v_fmac_f32_e32 v102, v51, v102
	v_div_scale_f32 v51, vcc, v89, v93, v89
	v_mul_f32_e32 v88, v51, v102
	v_fma_f32 v92, -v53, v88, v51
	v_fmac_f32_e32 v88, v92, v102
	v_pk_add_f32 v[100:101], v[100:101], 1.0 op_sel_hi:[1,0]
	v_fma_f32 v51, -v53, v88, v51
	v_div_scale_f32 v53, s[34:35], v101, v101, v69
	v_rcp_f32_e32 v92, v53
	v_div_fmas_f32 v51, v51, v102, v88
	v_div_fixup_f32 v51, v51, v93, v89
	v_pk_fma_f32 v[54:55], v[2:3], v[54:55], v[34:35]
	v_fma_f32 v88, -v53, v92, 1.0
	v_fmac_f32_e32 v92, v88, v92
	v_div_scale_f32 v88, vcc, v69, v101, v69
	v_mul_f32_e32 v89, v88, v92
	v_fma_f32 v93, -v53, v89, v88
	v_fmac_f32_e32 v89, v93, v92
	v_fma_f32 v53, -v53, v89, v88
	v_div_scale_f32 v88, s[34:35], v100, v100, v68
	v_rcp_f32_e32 v93, v88
	v_div_fmas_f32 v53, v53, v92, v89
	v_div_fixup_f32 v53, v53, v101, v69
	v_pk_fma_f32 v[54:55], v[10:11], v[60:61], v[54:55]
	v_fma_f32 v69, -v88, v93, 1.0
	v_fmac_f32_e32 v93, v69, v93
	v_div_scale_f32 v69, vcc, v68, v100, v68
	v_mul_f32_e32 v89, v69, v93
	v_fma_f32 v92, -v88, v89, v69
	v_fmac_f32_e32 v89, v92, v93
	v_fma_f32 v69, -v88, v89, v69
	v_div_fmas_f32 v69, v69, v93, v89
	v_div_fixup_f32 v68, v69, v100, v68
	v_cndmask_b32_e64 v92, 0, v68, s[12:13]
	v_mul_f32_e32 v68, 0xbfb8aa3b, v56
	v_mul_f32_e32 v69, 0xbfb8aa3b, v57
	v_exp_f32_e32 v68, v68
	v_exp_f32_e32 v69, v69
	v_pk_fma_f32 v[54:55], v[14:15], v[58:59], v[54:55]
	v_cndmask_b32_e64 v51, 0, v51, s[12:13]
	v_pk_fma_f32 v[54:55], v[30:31], v[78:79], v[54:55]
	v_pk_add_f32 v[68:69], v[68:69], 1.0 op_sel_hi:[1,0]
	v_mul_f32_e32 v88, 0xbfb8aa3b, v54
	v_div_scale_f32 v89, s[34:35], v68, v68, v56
	v_rcp_f32_e32 v93, v89
	v_exp_f32_e32 v88, v88
	v_cndmask_b32_e64 v44, 0, v44, s[12:13]
	v_cndmask_b32_e64 v53, 0, v53, s[12:13]
	v_fma_f32 v99, -v89, v93, 1.0
	v_fmac_f32_e32 v93, v99, v93
	v_div_scale_f32 v99, vcc, v56, v68, v56
	v_mul_f32_e32 v100, v99, v93
	v_fma_f32 v101, -v89, v100, v99
	v_fmac_f32_e32 v100, v101, v93
	v_fma_f32 v89, -v89, v100, v99
	v_div_scale_f32 v99, s[34:35], v69, v69, v57
	v_rcp_f32_e32 v101, v99
	v_div_fmas_f32 v89, v89, v93, v100
	v_div_fixup_f32 v56, v89, v68, v56
	v_mul_f32_e32 v89, 0xbfb8aa3b, v55
	v_fma_f32 v68, -v99, v101, 1.0
	v_exp_f32_e32 v89, v89
	v_fmac_f32_e32 v101, v68, v101
	v_div_scale_f32 v68, vcc, v57, v69, v57
	v_mul_f32_e32 v93, v68, v101
	v_fma_f32 v100, -v99, v93, v68
	v_fmac_f32_e32 v93, v100, v101
	v_pk_add_f32 v[88:89], v[88:89], 1.0 op_sel_hi:[1,0]
	v_fma_f32 v68, -v99, v93, v68
	v_div_scale_f32 v99, s[34:35], v89, v89, v55
	v_rcp_f32_e32 v100, v99
	v_div_fmas_f32 v68, v68, v101, v93
	v_div_fixup_f32 v57, v68, v69, v57
	v_cndmask_b32_e64 v57, 0, v57, s[12:13]
	v_fma_f32 v68, -v99, v100, 1.0
	v_fmac_f32_e32 v100, v68, v100
	v_div_scale_f32 v68, vcc, v55, v89, v55
	v_mul_f32_e32 v69, v68, v100
	v_fma_f32 v93, -v99, v69, v68
	v_fmac_f32_e32 v69, v93, v100
	v_div_scale_f32 v93, s[34:35], v88, v88, v54
	v_fma_f32 v68, -v99, v69, v68
	v_rcp_f32_e32 v99, v93
	v_div_fmas_f32 v68, v68, v100, v69
	v_div_fixup_f32 v55, v68, v89, v55
	v_cndmask_b32_e64 v56, 0, v56, s[12:13]
	v_fma_f32 v68, -v93, v99, 1.0
	v_fmac_f32_e32 v99, v68, v99
	v_div_scale_f32 v68, vcc, v54, v88, v54
	v_mul_f32_e32 v69, v68, v99
	v_fma_f32 v89, -v93, v69, v68
	v_fmac_f32_e32 v69, v89, v99
	v_fma_f32 v68, -v93, v69, v68
	v_div_fmas_f32 v68, v68, v99, v69
	v_div_fixup_f32 v54, v68, v88, v54
	v_cndmask_b32_e64 v54, 0, v54, s[12:13]
	v_bfe_u32 v68, v44, 16, 1
	v_bfe_u32 v69, v51, 16, 1
	v_bfe_u32 v88, v56, 16, 1
	v_bfe_u32 v89, v57, 16, 1
	v_add3_u32 v57, v57, v89, s39
	v_add3_u32 v56, v56, v88, s39
	v_add3_u32 v51, v51, v69, s39
	v_add3_u32 v44, v44, v68, s39
	v_bfe_u32 v69, v54, 16, 1
	v_bfe_u32 v89, v92, 16, 1
	v_cndmask_b32_e64 v55, 0, v55, s[12:13]
	v_lshrrev_b32_e32 v44, 16, v44
	v_lshrrev_b32_e32 v56, 16, v56
	v_bfe_u32 v88, v53, 16, 1
	v_add3_u32 v89, v92, v89, s39
	v_add3_u32 v54, v54, v69, s39
	v_bfe_u32 v68, v55, 16, 1
	v_add3_u32 v53, v53, v88, s39
	v_and_or_b32 v56, v54, s33, v56
	v_and_or_b32 v54, v89, s33, v44
	v_lshl_add_u64 v[88:89], v[64:65], 0, s[30:31]
	v_lshrrev_b32_e32 v51, 16, v51
	v_lshrrev_b32_e32 v57, 16, v57
	v_add3_u32 v55, v55, v68, s39
	v_add_co_u32_e32 v68, vcc, 0x15f00000, v88
	v_and_or_b32 v57, v55, s33, v57
	v_and_or_b32 v55, v53, s33, v51
	v_addc_co_u32_e32 v69, vcc, 0, v89, vcc
	global_store_dwordx4 v[68:69], v[54:57], off
	v_cmp_lt_i32_e64 s[12:13], s40, v50
	v_mov_b32_e32 v53, 0
	v_mov_b32_e32 v68, 0
	v_mov_b32_e32 v69, 0
	v_mov_b32_e32 v56, 0
	v_mov_b32_e32 v57, 0
	v_mov_b32_e32 v54, 0
	v_mov_b32_e32 v55, 0
	s_and_saveexec_b64 s[34:35], s[12:13]
	s_cbranch_execz .LBB0_3289
	s_waitcnt vmcnt(15)
	v_lshlrev_b32_e32 v52, 16, v110
	v_and_b32_e32 v68, 0xffff0000, v110
	v_lshlrev_b32_e32 v53, 16, v111
	v_and_b32_e32 v69, 0xffff0000, v111
	v_lshlrev_b32_e32 v56, 16, v112
	v_and_b32_e32 v54, 0xffff0000, v112
	v_lshlrev_b32_e32 v57, 16, v113
	v_and_b32_e32 v55, 0xffff0000, v113
; __device__ __forceinline__ unsigned pack2(float a, float b) { return (unsigned)f2bf(a) | ((unsigned)f2bf(b) << 16); }
; __device__ __forceinline__ float siluf(float x) { return x / (1.f + __expf(-x)); }
; #define UNPACK8(q, f)                                                                                   \
;   float f##0 = lo16(q.x), f##1 = hi16(q.x), f##2 = lo16(q.y), f##3 = hi16(q.y), f##4 = lo16(q.z),        \
;         f##5 = hi16(q.z), f##6 = lo16(q.w), f##7 = hi16(q.w)
; __device__ __forceinline__ void phase_ssd_conv(const Params& p, int layer) {
;     ...
;     for (int rr = 0; rr < 16; rr++) {
;       int t = tstart + rr;
;       float cur[8];
;       bool vt = t >= NPADR;
;       if (vt) {
;         u32x4 q = *(const u32x4*)(raw + (size_t)t * 2048 + cv);
;         UNPACK8(q, f);
;         cur[0] = f0; cur[1] = f1; cur[2] = f2; cur[3] = f3; cur[4] = f4; cur[5] = f5; cur[6] = f6; cur[7] = f7;
;       } else {
; #pragma unroll
;         for (int j = 0; j < 8; j++) cur[j] = 0.f;
;       }
;       float o[8];
; #pragma unroll
;       for (int j = 0; j < 8; j++) {
;         float s = bias[j] + w[0][j] * h[0][j] + w[1][j] * h[1][j] + w[2][j] * h[2][j] + w[3][j] * cur[j];
;         s = siluf(s);
;         if (cv < 1024 && !vt) s = 0.f;
;         o[j] = s;
;         h[0][j] = h[1][j]; h[1][j] = h[2][j]; h[2][j] = cur[j];
;       }
;       u32x4 r;
;       r.x = pack2(o[0], o[1]); r.y = pack2(o[2], o[3]); r.z = pack2(o[4], o[5]); r.w = pack2(o[6], o[7]);
;       *(u32x4*)(xc + (size_t)t * 2048 + cv) = r;
.LBB0_3289:
	s_or_b64 exec, exec, s[34:35]
	v_pk_fma_f32 v[74:75], v[4:5], v[74:75], v[36:37]
	v_pk_fma_f32 v[72:73], v[6:7], v[72:73], v[38:39]
	v_pk_fma_f32 v[74:75], v[24:25], v[90:91], v[74:75]
	v_pk_fma_f32 v[72:73], v[26:27], v[76:77], v[72:73]
	v_pk_fma_f32 v[74:75], v[16:17], v[84:85], v[74:75]
	v_pk_fma_f32 v[72:73], v[18:19], v[82:83], v[72:73]
	v_pk_fma_f32 v[74:75], v[20:21], v[52:53], v[74:75]
	v_pk_fma_f32 v[72:73], v[22:23], v[68:69], v[72:73]
	v_mul_f32_e32 v44, 0xbfb8aa3b, v74
	v_exp_f32_e32 v92, v44
	v_mul_f32_e32 v44, 0xbfb8aa3b, v75
	v_exp_f32_e32 v93, v44
	v_mul_f32_e32 v99, 0xbfb8aa3b, v72
	v_exp_f32_e32 v100, v99
	v_pk_fma_f32 v[62:63], v[0:1], v[62:63], v[32:33]
	v_pk_add_f32 v[92:93], v[92:93], 1.0 op_sel_hi:[1,0]
	v_pk_fma_f32 v[62:63], v[8:9], v[70:71], v[62:63]
	v_div_scale_f32 v44, s[34:35], v92, v92, v74
	v_rcp_f32_e32 v51, v44
	v_pk_fma_f32 v[62:63], v[12:13], v[80:81], v[62:63]
	s_or_b64 s[12:13], s[28:29], s[12:13]
	v_pk_fma_f32 v[62:63], v[28:29], v[56:57], v[62:63]
	v_fma_f32 v99, -v44, v51, 1.0
	v_fmac_f32_e32 v51, v99, v51
	v_div_scale_f32 v99, vcc, v74, v92, v74
	v_mul_f32_e32 v101, v99, v51
	v_fma_f32 v102, -v44, v101, v99
	v_fmac_f32_e32 v101, v102, v51
	v_fma_f32 v44, -v44, v101, v99
	v_div_scale_f32 v99, s[34:35], v93, v93, v75
	v_rcp_f32_e32 v102, v99
	v_div_fmas_f32 v44, v44, v51, v101
	v_div_fixup_f32 v44, v44, v92, v74
	v_mul_f32_e32 v92, 0xbfb8aa3b, v73
	v_exp_f32_e32 v101, v92
	v_fma_f32 v51, -v99, v102, 1.0
	v_fmac_f32_e32 v102, v51, v102
	v_div_scale_f32 v51, vcc, v75, v93, v75
	v_mul_f32_e32 v74, v51, v102
	v_fma_f32 v92, -v99, v74, v51
	v_pk_add_f32 v[100:101], v[100:101], 1.0 op_sel_hi:[1,0]
	v_fmac_f32_e32 v74, v92, v102
	v_div_scale_f32 v92, s[34:35], v101, v101, v73
	v_fma_f32 v51, -v99, v74, v51
	v_rcp_f32_e32 v99, v92
	v_div_fmas_f32 v51, v51, v102, v74
	v_div_fixup_f32 v51, v51, v93, v75
	v_pk_fma_f32 v[60:61], v[2:3], v[60:61], v[34:35]
	v_fma_f32 v74, -v92, v99, 1.0
	v_fmac_f32_e32 v99, v74, v99
	v_div_scale_f32 v74, vcc, v73, v101, v73
	v_mul_f32_e32 v75, v74, v99
	v_fma_f32 v93, -v92, v75, v74
	v_fmac_f32_e32 v75, v93, v99
	v_fma_f32 v74, -v92, v75, v74
	v_div_scale_f32 v92, s[34:35], v100, v100, v72
	v_rcp_f32_e32 v93, v92
	v_div_fmas_f32 v74, v74, v99, v75
	v_div_fixup_f32 v73, v74, v101, v73
	v_pk_fma_f32 v[60:61], v[10:11], v[58:59], v[60:61]
	v_fma_f32 v74, -v92, v93, 1.0
	v_fmac_f32_e32 v93, v74, v93
	v_div_scale_f32 v74, vcc, v72, v100, v72
	v_mul_f32_e32 v75, v74, v93
	v_fma_f32 v99, -v92, v75, v74
	v_fmac_f32_e32 v75, v99, v93
	v_fma_f32 v74, -v92, v75, v74
	v_div_fmas_f32 v74, v74, v93, v75
	v_div_fixup_f32 v72, v74, v100, v72
	v_cndmask_b32_e64 v92, 0, v72, s[12:13]
	v_cndmask_b32_e64 v93, 0, v73, s[12:13]
	v_mul_f32_e32 v72, 0xbfb8aa3b, v62
	v_mul_f32_e32 v73, 0xbfb8aa3b, v63
	v_exp_f32_e32 v72, v72
	v_exp_f32_e32 v73, v73
	v_pk_fma_f32 v[60:61], v[14:15], v[78:79], v[60:61]
	v_cndmask_b32_e64 v51, 0, v51, s[12:13]
	v_pk_fma_f32 v[60:61], v[30:31], v[54:55], v[60:61]
	v_pk_add_f32 v[72:73], v[72:73], 1.0 op_sel_hi:[1,0]
	v_mul_f32_e32 v74, 0xbfb8aa3b, v60
	v_div_scale_f32 v75, s[34:35], v72, v72, v62
	v_rcp_f32_e32 v99, v75
	v_exp_f32_e32 v74, v74
	v_cndmask_b32_e64 v44, 0, v44, s[12:13]
	v_fma_f32 v100, -v75, v99, 1.0
	v_fmac_f32_e32 v99, v100, v99
	v_div_scale_f32 v100, vcc, v62, v72, v62
	v_mul_f32_e32 v101, v100, v99
	v_fma_f32 v102, -v75, v101, v100
	v_fmac_f32_e32 v101, v102, v99
	v_fma_f32 v75, -v75, v101, v100
	v_div_scale_f32 v100, s[34:35], v73, v73, v63
	v_rcp_f32_e32 v102, v100
	v_div_fmas_f32 v75, v75, v99, v101
	v_div_fixup_f32 v62, v75, v72, v62
	v_mul_f32_e32 v75, 0xbfb8aa3b, v61
	v_fma_f32 v72, -v100, v102, 1.0
	v_exp_f32_e32 v75, v75
	v_fmac_f32_e32 v102, v72, v102
	v_div_scale_f32 v72, vcc, v63, v73, v63
	v_mul_f32_e32 v99, v72, v102
	v_fma_f32 v101, -v100, v99, v72
	v_fmac_f32_e32 v99, v101, v102
	v_pk_add_f32 v[74:75], v[74:75], 1.0 op_sel_hi:[1,0]
	v_fma_f32 v72, -v100, v99, v72
	v_div_scale_f32 v100, s[34:35], v75, v75, v61
	v_rcp_f32_e32 v101, v100
	v_div_fmas_f32 v72, v72, v102, v99
	v_div_fixup_f32 v63, v72, v73, v63
	v_cndmask_b32_e64 v63, 0, v63, s[12:13]
	v_fma_f32 v72, -v100, v101, 1.0
	v_fmac_f32_e32 v101, v72, v101
	v_div_scale_f32 v72, vcc, v61, v75, v61
	v_mul_f32_e32 v73, v72, v101
	v_fma_f32 v99, -v100, v73, v72
	v_fmac_f32_e32 v73, v99, v101
	v_div_scale_f32 v99, s[34:35], v74, v74, v60
	v_fma_f32 v72, -v100, v73, v72
	v_rcp_f32_e32 v100, v99
	v_div_fmas_f32 v72, v72, v101, v73
	v_div_fixup_f32 v61, v72, v75, v61
	v_cndmask_b32_e64 v62, 0, v62, s[12:13]
	v_fma_f32 v72, -v99, v100, 1.0
	v_fmac_f32_e32 v100, v72, v100
	v_div_scale_f32 v72, vcc, v60, v74, v60
	v_mul_f32_e32 v73, v72, v100
	v_fma_f32 v75, -v99, v73, v72
	v_fmac_f32_e32 v73, v75, v100
	v_fma_f32 v72, -v99, v73, v72
	v_div_fmas_f32 v72, v72, v100, v73
	v_div_fixup_f32 v60, v72, v74, v60
	v_cndmask_b32_e64 v60, 0, v60, s[12:13]
	v_cndmask_b32_e64 v61, 0, v61, s[12:13]
	v_bfe_u32 v72, v44, 16, 1
	v_bfe_u32 v73, v51, 16, 1
	v_bfe_u32 v74, v62, 16, 1
	v_bfe_u32 v75, v63, 16, 1
	v_add3_u32 v63, v63, v75, s39
	v_add3_u32 v62, v62, v74, s39
	v_add3_u32 v51, v51, v73, s39
	v_add3_u32 v44, v44, v72, s39
	v_bfe_u32 v72, v61, 16, 1
	v_bfe_u32 v73, v60, 16, 1
	v_bfe_u32 v74, v93, 16, 1
	v_bfe_u32 v75, v92, 16, 1
	v_lshrrev_b32_e32 v44, 16, v44
	v_lshrrev_b32_e32 v51, 16, v51
	v_lshrrev_b32_e32 v62, 16, v62
	v_lshrrev_b32_e32 v63, 16, v63
	v_add3_u32 v75, v92, v75, s39
	v_add3_u32 v74, v93, v74, s39
	v_add3_u32 v60, v60, v73, s39
	v_add3_u32 v61, v61, v72, s39
	v_add_co_u32_e32 v72, vcc, 0x15f01000, v88
	v_and_or_b32 v63, v61, s33, v63
	v_and_or_b32 v62, v60, s33, v62
	v_and_or_b32 v61, v74, s33, v51
	v_and_or_b32 v60, v75, s33, v44
	v_addc_co_u32_e32 v73, vcc, 0, v89, vcc
	v_add_u32_e32 v44, 2, v50
	global_store_dwordx4 v[72:73], v[60:63], off
	v_cmp_lt_i32_e64 s[12:13], s38, v44
	v_mov_b32_e32 v92, 0
	v_mov_b32_e32 v74, 0
	v_mov_b32_e32 v75, 0
	v_mov_b32_e32 v72, 0
	v_mov_b32_e32 v73, 0
	v_mov_b32_e32 v62, 0
	v_mov_b32_e32 v63, 0
	v_mov_b32_e32 v60, 0
	v_mov_b32_e32 v61, 0
	s_and_saveexec_b64 s[34:35], s[12:13]
	s_cbranch_execz .LBB0_3291
	s_waitcnt vmcnt(15)
	v_lshlrev_b32_e32 v74, 16, v114
	v_and_b32_e32 v72, 0xffff0000, v114
	v_lshlrev_b32_e32 v75, 16, v115
	v_and_b32_e32 v73, 0xffff0000, v115
	v_lshlrev_b32_e32 v62, 16, v116
	v_and_b32_e32 v60, 0xffff0000, v116
	v_lshlrev_b32_e32 v63, 16, v117
	v_and_b32_e32 v61, 0xffff0000, v117
; __device__ __forceinline__ unsigned pack2(float a, float b) { return (unsigned)f2bf(a) | ((unsigned)f2bf(b) << 16); }
; __device__ __forceinline__ float siluf(float x) { return x / (1.f + __expf(-x)); }
; #define UNPACK8(q, f)                                                                                   \
;   float f##0 = lo16(q.x), f##1 = hi16(q.x), f##2 = lo16(q.y), f##3 = hi16(q.y), f##4 = lo16(q.z),        \
;         f##5 = hi16(q.z), f##6 = lo16(q.w), f##7 = hi16(q.w)
; __device__ __forceinline__ void phase_ssd_conv(const Params& p, int layer) {
;     ...
;     for (int rr = 0; rr < 16; rr++) {
;       int t = tstart + rr;
;       float cur[8];
;       bool vt = t >= NPADR;
;       if (vt) {
;         u32x4 q = *(const u32x4*)(raw + (size_t)t * 2048 + cv);
;         UNPACK8(q, f);
;         cur[0] = f0; cur[1] = f1; cur[2] = f2; cur[3] = f3; cur[4] = f4; cur[5] = f5; cur[6] = f6; cur[7] = f7;
;       } else {
; #pragma unroll
;         for (int j = 0; j < 8; j++) cur[j] = 0.f;
;       }
;       float o[8];
; #pragma unroll
;       for (int j = 0; j < 8; j++) {
;         float s = bias[j] + w[0][j] * h[0][j] + w[1][j] * h[1][j] + w[2][j] * h[2][j] + w[3][j] * cur[j];
;         s = siluf(s);
;         if (cv < 1024 && !vt) s = 0.f;
;         o[j] = s;
;         h[0][j] = h[1][j]; h[1][j] = h[2][j]; h[2][j] = cur[j];
;       }
;       u32x4 r;
;       r.x = pack2(o[0], o[1]); r.y = pack2(o[2], o[3]); r.z = pack2(o[4], o[5]); r.w = pack2(o[6], o[7]);
;       *(u32x4*)(xc + (size_t)t * 2048 + cv) = r;
.LBB0_3291:
	s_or_b64 exec, exec, s[34:35]
	v_pk_fma_f32 v[90:91], v[4:5], v[90:91], v[36:37]
	v_pk_fma_f32 v[76:77], v[6:7], v[76:77], v[38:39]
	v_pk_fma_f32 v[90:91], v[24:25], v[84:85], v[90:91]
	v_pk_fma_f32 v[76:77], v[26:27], v[82:83], v[76:77]
	v_pk_fma_f32 v[90:91], v[16:17], v[52:53], v[90:91]
	v_pk_fma_f32 v[76:77], v[18:19], v[68:69], v[76:77]
	v_pk_fma_f32 v[90:91], v[20:21], v[74:75], v[90:91]
	v_pk_fma_f32 v[76:77], v[22:23], v[72:73], v[76:77]
	v_mul_f32_e32 v44, 0xbfb8aa3b, v90
	v_exp_f32_e32 v100, v44
	v_mul_f32_e32 v44, 0xbfb8aa3b, v91
	v_exp_f32_e32 v101, v44
	v_mul_f32_e32 v93, 0xbfb8aa3b, v76
	v_exp_f32_e32 v102, v93
	v_pk_fma_f32 v[70:71], v[0:1], v[70:71], v[32:33]
	v_pk_add_f32 v[100:101], v[100:101], 1.0 op_sel_hi:[1,0]
	v_pk_fma_f32 v[70:71], v[8:9], v[80:81], v[70:71]
	v_div_scale_f32 v44, s[34:35], v100, v100, v90
	v_rcp_f32_e32 v51, v44
	v_pk_fma_f32 v[70:71], v[12:13], v[56:57], v[70:71]
	s_or_b64 s[12:13], s[28:29], s[12:13]
	v_pk_fma_f32 v[70:71], v[28:29], v[62:63], v[70:71]
	v_fma_f32 v93, -v44, v51, 1.0
	v_fmac_f32_e32 v51, v93, v51
	v_div_scale_f32 v93, vcc, v90, v100, v90
	v_mul_f32_e32 v99, v93, v51
	v_fma_f32 v103, -v44, v99, v93
	v_fmac_f32_e32 v99, v103, v51
	v_fma_f32 v44, -v44, v99, v93
	v_div_scale_f32 v93, s[34:35], v101, v101, v91
	v_rcp_f32_e32 v104, v93
	v_div_fmas_f32 v44, v44, v51, v99
	v_mul_f32_e32 v99, 0xbfb8aa3b, v77
	v_exp_f32_e32 v103, v99
	v_fma_f32 v51, -v93, v104, 1.0
	v_fmac_f32_e32 v104, v51, v104
	v_div_scale_f32 v51, vcc, v91, v101, v91
	v_div_fixup_f32 v44, v44, v100, v90
	v_mul_f32_e32 v90, v51, v104
	v_fma_f32 v99, -v93, v90, v51
	v_fmac_f32_e32 v90, v99, v104
	v_pk_add_f32 v[102:103], v[102:103], 1.0 op_sel_hi:[1,0]
	v_fma_f32 v51, -v93, v90, v51
	v_div_scale_f32 v93, s[34:35], v103, v103, v77
	v_rcp_f32_e32 v99, v93
	v_div_fmas_f32 v51, v51, v104, v90
	v_div_fixup_f32 v51, v51, v101, v91
	v_pk_fma_f32 v[58:59], v[2:3], v[58:59], v[34:35]
	v_fma_f32 v90, -v93, v99, 1.0
	v_fmac_f32_e32 v99, v90, v99
	v_div_scale_f32 v90, vcc, v77, v103, v77
	v_mul_f32_e32 v91, v90, v99
	v_fma_f32 v100, -v93, v91, v90
	v_fmac_f32_e32 v91, v100, v99
	v_fma_f32 v90, -v93, v91, v90
	v_div_scale_f32 v93, s[34:35], v102, v102, v76
	v_rcp_f32_e32 v100, v93
	v_div_fmas_f32 v90, v90, v99, v91
	v_div_fixup_f32 v77, v90, v103, v77
	v_pk_fma_f32 v[58:59], v[10:11], v[78:79], v[58:59]
	v_fma_f32 v90, -v93, v100, 1.0
	v_fmac_f32_e32 v100, v90, v100
	v_div_scale_f32 v90, vcc, v76, v102, v76
	v_mul_f32_e32 v91, v90, v100
	v_fma_f32 v99, -v93, v91, v90
	v_fmac_f32_e32 v91, v99, v100
	v_fma_f32 v90, -v93, v91, v90
	v_div_fmas_f32 v90, v90, v100, v91
	v_div_fixup_f32 v76, v90, v102, v76
	v_cndmask_b32_e64 v93, 0, v76, s[12:13]
	v_cndmask_b32_e64 v99, 0, v77, s[12:13]
	v_mul_f32_e32 v76, 0xbfb8aa3b, v70
	v_mul_f32_e32 v77, 0xbfb8aa3b, v71
	v_exp_f32_e32 v76, v76
	v_exp_f32_e32 v77, v77
	v_pk_fma_f32 v[58:59], v[14:15], v[54:55], v[58:59]
	v_cndmask_b32_e64 v51, 0, v51, s[12:13]
	v_pk_fma_f32 v[58:59], v[30:31], v[60:61], v[58:59]
	v_pk_add_f32 v[76:77], v[76:77], 1.0 op_sel_hi:[1,0]
	v_mul_f32_e32 v90, 0xbfb8aa3b, v58
	v_div_scale_f32 v91, s[34:35], v76, v76, v70
	v_rcp_f32_e32 v100, v91
	v_exp_f32_e32 v90, v90
	v_cndmask_b32_e64 v44, 0, v44, s[12:13]
	v_fma_f32 v101, -v91, v100, 1.0
	v_fmac_f32_e32 v100, v101, v100
	v_div_scale_f32 v101, vcc, v70, v76, v70
	v_mul_f32_e32 v102, v101, v100
	v_fma_f32 v103, -v91, v102, v101
	v_fmac_f32_e32 v102, v103, v100
	v_fma_f32 v91, -v91, v102, v101
	v_div_scale_f32 v101, s[34:35], v77, v77, v71
	v_rcp_f32_e32 v103, v101
	v_div_fmas_f32 v91, v91, v100, v102
	v_div_fixup_f32 v70, v91, v76, v70
	v_mul_f32_e32 v91, 0xbfb8aa3b, v59
	v_fma_f32 v76, -v101, v103, 1.0
	v_exp_f32_e32 v91, v91
	v_fmac_f32_e32 v103, v76, v103
	v_div_scale_f32 v76, vcc, v71, v77, v71
	v_mul_f32_e32 v100, v76, v103
	v_fma_f32 v102, -v101, v100, v76
	v_fmac_f32_e32 v100, v102, v103
	v_pk_add_f32 v[90:91], v[90:91], 1.0 op_sel_hi:[1,0]
	v_fma_f32 v76, -v101, v100, v76
	v_div_scale_f32 v101, s[34:35], v91, v91, v59
	v_rcp_f32_e32 v102, v101
	v_div_fmas_f32 v76, v76, v103, v100
	v_div_fixup_f32 v71, v76, v77, v71
	v_cndmask_b32_e64 v70, 0, v70, s[12:13]
	v_fma_f32 v76, -v101, v102, 1.0
	v_fmac_f32_e32 v102, v76, v102
	v_div_scale_f32 v76, vcc, v59, v91, v59
	v_mul_f32_e32 v77, v76, v102
	v_fma_f32 v100, -v101, v77, v76
	v_fmac_f32_e32 v77, v100, v102
	v_div_scale_f32 v100, s[34:35], v90, v90, v58
	v_fma_f32 v76, -v101, v77, v76
	v_rcp_f32_e32 v101, v100
	v_div_fmas_f32 v76, v76, v102, v77
	v_div_fixup_f32 v59, v76, v91, v59
	v_cndmask_b32_e64 v71, 0, v71, s[12:13]
	v_fma_f32 v76, -v100, v101, 1.0
	v_fmac_f32_e32 v101, v76, v101
	v_div_scale_f32 v76, vcc, v58, v90, v58
	v_mul_f32_e32 v77, v76, v101
	v_fma_f32 v91, -v100, v77, v76
	v_fmac_f32_e32 v77, v91, v101
	v_fma_f32 v76, -v100, v77, v76
	v_div_fmas_f32 v76, v76, v101, v77
	v_div_fixup_f32 v58, v76, v90, v58
	v_cndmask_b32_e64 v58, 0, v58, s[12:13]
	v_bfe_u32 v77, v51, 16, 1
	v_bfe_u32 v90, v70, 16, 1
	v_cndmask_b32_e64 v59, 0, v59, s[12:13]
	v_bfe_u32 v76, v44, 16, 1
	v_bfe_u32 v91, v71, 16, 1
	v_add3_u32 v70, v70, v90, s39
	v_add3_u32 v51, v51, v77, s39
	v_bfe_u32 v77, v58, 16, 1
	v_add3_u32 v71, v71, v91, s39
	v_add3_u32 v44, v44, v76, s39
	v_lshrrev_b32_e32 v70, 16, v70
	v_bfe_u32 v76, v59, 16, 1
	v_bfe_u32 v90, v99, 16, 1
	v_bfe_u32 v91, v93, 16, 1
	v_add3_u32 v58, v58, v77, s39
	v_lshrrev_b32_e32 v44, 16, v44
	v_lshrrev_b32_e32 v51, 16, v51
	v_lshrrev_b32_e32 v71, 16, v71
	v_add3_u32 v91, v93, v91, s39
	v_add3_u32 v90, v99, v90, s39
	v_add3_u32 v59, v59, v76, s39
	v_and_or_b32 v102, v58, s33, v70
	v_add_co_u32_e32 v58, vcc, 0x15f02000, v88
	v_and_or_b32 v103, v59, s33, v71
	v_and_or_b32 v101, v90, s33, v51
	v_and_or_b32 v100, v91, s33, v44
	v_addc_co_u32_e32 v59, vcc, 0, v89, vcc
	v_add_u32_e32 v44, 3, v50
	global_store_dwordx4 v[58:59], v[100:103], off
	v_cmp_lt_i32_e64 s[12:13], s38, v44
	v_mov_b32_e32 v93, 0
	v_mov_b32_e32 v76, 0
	v_mov_b32_e32 v77, 0
	v_mov_b32_e32 v70, 0
	v_mov_b32_e32 v71, 0
	v_mov_b32_e32 v58, 0
	v_mov_b32_e32 v59, 0
	s_and_saveexec_b64 s[34:35], s[12:13]
	s_cbranch_execz .LBB0_3284
	s_waitcnt vmcnt(15)
	v_lshlrev_b32_e32 v92, 16, v118
	v_and_b32_e32 v76, 0xffff0000, v118
	v_lshlrev_b32_e32 v93, 16, v119
	v_and_b32_e32 v77, 0xffff0000, v119
	v_lshlrev_b32_e32 v70, 16, v120
	v_and_b32_e32 v58, 0xffff0000, v120
	v_lshlrev_b32_e32 v71, 16, v121
	v_and_b32_e32 v59, 0xffff0000, v121
	s_branch .LBB0_3284
